# GEMM k-loops: activation fragment kept stationary for 8 consecutive MFMAs (operand-stationary order), waits recomputed
# baseline (speedup 1.0000x reference)
.LBB0_231:
	s_add_i32 s47, s48, 0x8000
	s_and_b32 s27, s48, 0x8000
	s_and_b32 s50, s47, 0x8000
	s_add_i32 s48, s27, 0
	s_add_i32 s27, s50, 0
	s_add_u32 s70, s27, s71
	s_mov_b32 m0, s70
	s_waitcnt vmcnt(0) lgkmcnt(0)
	s_barrier
	global_load_lds_dwordx4 v244, s[96:97]
	s_add_u32 m0, s70, 0x4000
	s_nop 0
	global_load_lds_dwordx4 v245, s[72:73]
	s_add_u32 m0, s70, 0x1000
	s_nop 0
	global_load_lds_dwordx4 v246, s[96:97]
	s_add_u32 m0, s70, 0x5000
	s_nop 0
	global_load_lds_dwordx4 v247, s[72:73]
	s_add_u32 m0, s70, 0x2000
	s_nop 0
	global_load_lds_dwordx4 v248, s[96:97]
	s_add_u32 m0, s70, 0x6000
	s_nop 0
	global_load_lds_dwordx4 v249, s[72:73]
	s_add_u32 m0, s70, 0x3000
	s_nop 0
	global_load_lds_dwordx4 v250, s[96:97]
	s_add_u32 m0, s70, 0x7000
	s_nop 0
	global_load_lds_dwordx4 v251, s[72:73]
	s_add_u32 s96, s96, 0x80
	s_addc_u32 s97, s97, 0
	s_add_u32 s72, s72, 0x80
	s_addc_u32 s73, s73, 0
	v_add3_u32 v145, s48, v86, v87
	v_add3_u32 v208, s48, v87, v88
	v_add3_u32 v209, s48, v86, v89
	v_add3_u32 v210, s48, v88, v89
	ds_read_b128 v[104:107], v208
	ds_read_b128 v[100:103], v145 offset:16384
	ds_read_b128 v[108:111], v145 offset:18432
	ds_read_b128 v[164:167], v208 offset:2048
	ds_read_b128 v[112:115], v145 offset:20480
	ds_read_b128 v[116:119], v145 offset:22528
	ds_read_b128 v[120:123], v145 offset:24576
	ds_read_b128 v[124:127], v145 offset:26624
	ds_read_b128 v[128:131], v145 offset:28672
	ds_read_b128 v[132:135], v145 offset:30720
	ds_read_b128 v[200:203], v210
	ds_read_b128 v[168:171], v209 offset:16384
	ds_read_b128 v[172:175], v209 offset:18432
	ds_read_b128 v[204:207], v210 offset:2048
	ds_read_b128 v[176:179], v209 offset:20480
	ds_read_b128 v[180:183], v209 offset:22528
	ds_read_b128 v[184:187], v209 offset:24576
	ds_read_b128 v[188:191], v209 offset:26624
	ds_read_b128 v[192:195], v209 offset:28672
	ds_read_b128 v[196:199], v209 offset:30720
	s_add_u32 s24, s24, 0x80
	s_addc_u32 s25, s25, 0
	s_cmpk_eq_i32 s24, 0x780
	s_mov_b32 s48, s47
	s_waitcnt lgkmcnt(15)
	v_mfma_f32_16x16x32_bf16 v[60:63], v[100:103], v[104:107], v[60:63]
	v_mfma_f32_16x16x32_bf16 v[56:59], v[108:111], v[104:107], v[56:59]
	v_mfma_f32_16x16x32_bf16 v[52:55], v[112:115], v[104:107], v[52:55]
	s_waitcnt lgkmcnt(14)
	v_mfma_f32_16x16x32_bf16 v[48:51], v[116:119], v[104:107], v[48:51]
	s_waitcnt lgkmcnt(13)
	v_mfma_f32_16x16x32_bf16 v[44:47], v[120:123], v[104:107], v[44:47]
	s_waitcnt lgkmcnt(12)
	v_mfma_f32_16x16x32_bf16 v[40:43], v[124:127], v[104:107], v[40:43]
	s_waitcnt lgkmcnt(11)
	v_mfma_f32_16x16x32_bf16 v[36:39], v[128:131], v[104:107], v[36:39]
	s_waitcnt lgkmcnt(10)
	v_mfma_f32_16x16x32_bf16 v[32:35], v[132:135], v[104:107], v[32:35]
	v_mfma_f32_16x16x32_bf16 v[24:27], v[100:103], v[164:167], v[24:27]
	v_mfma_f32_16x16x32_bf16 v[20:23], v[108:111], v[164:167], v[20:23]
	v_mfma_f32_16x16x32_bf16 v[16:19], v[112:115], v[164:167], v[16:19]
	v_mfma_f32_16x16x32_bf16 v[12:15], v[116:119], v[164:167], v[12:15]
	v_mfma_f32_16x16x32_bf16 v[8:11], v[120:123], v[164:167], v[8:11]
	v_mfma_f32_16x16x32_bf16 v[4:7], v[124:127], v[164:167], v[4:7]
	v_mfma_f32_16x16x32_bf16 v[0:3], v[128:131], v[164:167], v[0:3]
	v_mfma_f32_16x16x32_bf16 v[28:31], v[132:135], v[164:167], v[28:31]
	s_waitcnt lgkmcnt(8)
	v_mfma_f32_16x16x32_bf16 v[60:63], v[168:171], v[200:203], v[60:63]
	s_waitcnt lgkmcnt(7)
	v_mfma_f32_16x16x32_bf16 v[56:59], v[172:175], v[200:203], v[56:59]
	s_waitcnt lgkmcnt(5)
	v_mfma_f32_16x16x32_bf16 v[52:55], v[176:179], v[200:203], v[52:55]
	s_waitcnt lgkmcnt(4)
	v_mfma_f32_16x16x32_bf16 v[48:51], v[180:183], v[200:203], v[48:51]
	s_waitcnt lgkmcnt(3)
	v_mfma_f32_16x16x32_bf16 v[44:47], v[184:187], v[200:203], v[44:47]
	s_waitcnt lgkmcnt(2)
	v_mfma_f32_16x16x32_bf16 v[40:43], v[188:191], v[200:203], v[40:43]
	s_waitcnt lgkmcnt(1)
	v_mfma_f32_16x16x32_bf16 v[36:39], v[192:195], v[200:203], v[36:39]
	s_waitcnt lgkmcnt(0)
	v_mfma_f32_16x16x32_bf16 v[32:35], v[196:199], v[200:203], v[32:35]
	v_mfma_f32_16x16x32_bf16 v[24:27], v[168:171], v[204:207], v[24:27]
	v_mfma_f32_16x16x32_bf16 v[20:23], v[172:175], v[204:207], v[20:23]
	v_mfma_f32_16x16x32_bf16 v[16:19], v[176:179], v[204:207], v[16:19]
	v_mfma_f32_16x16x32_bf16 v[12:15], v[180:183], v[204:207], v[12:15]
	v_mfma_f32_16x16x32_bf16 v[8:11], v[184:187], v[204:207], v[8:11]
	v_mfma_f32_16x16x32_bf16 v[4:7], v[188:191], v[204:207], v[4:7]
	v_mfma_f32_16x16x32_bf16 v[0:3], v[192:195], v[204:207], v[0:3]
	v_mfma_f32_16x16x32_bf16 v[28:31], v[196:199], v[204:207], v[28:31]
	s_cbranch_scc0 .LBB0_231
	v_add_u32_e32 v64, s27, v86
	v_add_u32_e32 v136, v64, v87
	v_add3_u32 v108, s27, v87, v88
	s_waitcnt vmcnt(0)
	s_barrier
	ds_read_b128 v[80:83], v136 offset:16384
	ds_read_b128 v[100:103], v136 offset:18432
	ds_read_b128 v[104:107], v108
	ds_read_b128 v[108:111], v108 offset:2048
	ds_read_b128 v[112:115], v136 offset:20480
	ds_read_b128 v[116:119], v136 offset:22528
	ds_read_b128 v[128:131], v136 offset:28672
	s_waitcnt lgkmcnt(2)
	v_mfma_f32_16x16x32_bf16 v[120:123], v[112:115], v[104:107], v[52:55]
	s_nop 2
	ds_read_b128 v[52:55], v136 offset:24576
	ds_read_b128 v[124:127], v136 offset:26624
	s_cmp_gt_i32 s26, 11
	s_waitcnt lgkmcnt(0)
	v_mfma_f32_16x16x32_bf16 v[132:135], v[124:127], v[104:107], v[40:43]
	s_nop 2
	ds_read_b128 v[40:43], v136 offset:30720
	s_cselect_b64 s[24:25], -1, 0
	s_cmp_lt_i32 s26, 12
	v_mfma_f32_16x16x32_bf16 v[60:63], v[80:83], v[104:107], v[60:63]
	s_cselect_b64 s[48:49], -1, 0
	v_mfma_f32_16x16x32_bf16 v[56:59], v[100:103], v[104:107], v[56:59]
	v_mfma_f32_16x16x32_bf16 v[48:51], v[116:119], v[104:107], v[48:51]
	v_mfma_f32_16x16x32_bf16 v[44:47], v[52:55], v[104:107], v[44:47]
	v_mfma_f32_16x16x32_bf16 v[136:139], v[128:131], v[104:107], v[36:39]
	s_waitcnt lgkmcnt(0)
	v_mfma_f32_16x16x32_bf16 v[32:35], v[40:43], v[104:107], v[32:35]
	v_mfma_f32_16x16x32_bf16 v[104:107], v[52:55], v[108:111], v[8:11]
	s_nop 2
	v_add_u32_e32 v8, v64, v89
	v_mfma_f32_16x16x32_bf16 v[24:27], v[80:83], v[108:111], v[24:27]
	v_add3_u32 v9, s27, v89, v88
	v_lshl_or_b32 v64, s26, 7, v90
	s_sub_i32 s26, s26, 18
	v_mfma_f32_16x16x32_bf16 v[80:83], v[112:115], v[108:111], v[16:19]
	s_cmp_lt_u32 s26, 8
	s_cselect_b64 s[26:27], -1, 0
	s_or_b64 s[48:49], s[48:49], s[26:27]
	v_mfma_f32_16x16x32_bf16 v[112:115], v[124:127], v[108:111], v[4:7]
	s_mov_b64 s[26:27], -1
	s_andn2_b64 vcc, exec, s[48:49]
	s_nop 0
	ds_read_b128 v[4:7], v8 offset:16384
	v_mfma_f32_16x16x32_bf16 v[20:23], v[100:103], v[108:111], v[20:23]
	v_mfma_f32_16x16x32_bf16 v[100:103], v[116:119], v[108:111], v[12:15]
	v_mfma_f32_16x16x32_bf16 v[116:119], v[128:131], v[108:111], v[0:3]
	ds_read_b128 v[124:127], v8 offset:18432
	s_nop 1
	ds_read_b128 v[0:3], v9
	ds_read_b128 v[128:131], v9 offset:2048
	ds_read_b128 v[140:143], v8 offset:22528
	ds_read_b128 v[146:149], v8 offset:28672
	s_waitcnt lgkmcnt(3)
	v_mfma_f32_16x16x32_bf16 v[52:55], v[4:7], v[0:3], v[60:63]
	s_nop 2
	ds_read_b128 v[60:63], v8 offset:20480
	v_mfma_f32_16x16x32_bf16 v[108:111], v[40:43], v[108:111], v[28:31]
	s_waitcnt lgkmcnt(0)
	v_mfma_f32_16x16x32_bf16 v[36:39], v[60:63], v[0:3], v[120:123]
	s_nop 2
	ds_read_b128 v[120:123], v8 offset:24576
	v_mfma_f32_16x16x32_bf16 v[40:43], v[140:143], v[0:3], v[48:51]
	s_nop 2
	ds_read_b128 v[48:51], v8 offset:26624
	s_waitcnt lgkmcnt(0)
	v_mfma_f32_16x16x32_bf16 v[16:19], v[48:51], v[0:3], v[132:135]
	s_nop 2
	ds_read_b128 v[132:135], v8 offset:30720
	v_mfma_f32_16x16x32_bf16 v[56:59], v[124:127], v[0:3], v[56:59]
	v_mfma_f32_16x16x32_bf16 v[12:15], v[120:123], v[0:3], v[44:47]
	v_mfma_f32_16x16x32_bf16 v[8:11], v[146:149], v[0:3], v[136:139]
	s_waitcnt lgkmcnt(0)
	v_mfma_f32_16x16x32_bf16 v[0:3], v[132:135], v[0:3], v[32:35]
	v_mfma_f32_16x16x32_bf16 v[28:31], v[4:7], v[128:131], v[24:27]
	v_mfma_f32_16x16x32_bf16 v[20:23], v[124:127], v[128:131], v[20:23]
	v_mfma_f32_16x16x32_bf16 v[4:7], v[60:63], v[128:131], v[80:83]
	v_mfma_f32_16x16x32_bf16 v[24:27], v[140:143], v[128:131], v[100:103]
	s_nop 1
	v_lshl_add_u32 v80, s46, 7, v85
	v_mfma_f32_16x16x32_bf16 v[32:35], v[120:123], v[128:131], v[104:107]
	v_mfma_f32_16x16x32_bf16 v[44:47], v[48:51], v[128:131], v[112:115]
	v_mfma_f32_16x16x32_bf16 v[48:51], v[146:149], v[128:131], v[116:119]
	v_mfma_f32_16x16x32_bf16 v[60:63], v[132:135], v[128:131], v[108:111]
	s_cbranch_vccz .LBB0_240
	s_and_b32 s47, 0xffff, s45
	s_cmp_gt_u32 s47, 17
	s_cbranch_scc0 .LBB0_237
	s_cmp_eq_u32 s47, 26
	s_cselect_b64 s[26:27], -1, 0
	s_and_b64 s[48:49], s[10:11], s[26:27]
	s_and_saveexec_b64 s[26:27], s[48:49]
	s_cbranch_execz .LBB0_236
	global_load_dwordx4 v[100:103], v[72:73], off
	v_mad_i64_i32 v[82:83], s[48:49], v80, s28, v[70:71]
	v_or_b32_e32 v81, 16, v80
	s_waitcnt vmcnt(0)
	v_pk_add_f32 v[102:103], v[54:55], v[102:103]
	v_pk_add_f32 v[100:101], v[52:53], v[100:101]
	global_store_dwordx4 v[82:83], v[100:103], off
	global_load_dwordx4 v[100:103], v[72:73], off offset:16
	v_mad_i64_i32 v[82:83], s[48:49], v80, s28, v[74:75]
	s_waitcnt vmcnt(0)
	v_pk_add_f32 v[102:103], v[58:59], v[102:103]
	v_pk_add_f32 v[100:101], v[56:57], v[100:101]
	global_store_dwordx4 v[82:83], v[100:103], off
	global_load_dwordx4 v[100:103], v[72:73], off
	v_mad_i64_i32 v[82:83], s[48:49], v81, s28, v[70:71]
	s_waitcnt vmcnt(0)
	v_pk_add_f32 v[102:103], v[30:31], v[102:103]
	v_pk_add_f32 v[100:101], v[28:29], v[100:101]
	global_store_dwordx4 v[82:83], v[100:103], off
	global_load_dwordx4 v[100:103], v[72:73], off offset:16
	v_mad_i64_i32 v[82:83], s[48:49], v81, s28, v[74:75]
	s_waitcnt vmcnt(0)
	v_pk_add_f32 v[102:103], v[22:23], v[102:103]
	v_pk_add_f32 v[100:101], v[20:21], v[100:101]
	global_store_dwordx4 v[82:83], v[100:103], off

.LBB0_855:
	s_add_i32 s45, s43, 0x8000
	s_and_b32 s44, s45, 0x8000
	s_add_i32 s44, s44, 0
	s_add_u32 s86, s44, s87
	s_mov_b32 m0, s86
	s_waitcnt vmcnt(0) lgkmcnt(0)
	s_barrier
	global_load_lds_dwordx4 v244, s[96:97]
	s_add_u32 m0, s86, 0x4000
	s_nop 0
	global_load_lds_dwordx4 v245, s[88:89]
	s_add_u32 m0, s86, 0x1000
	s_nop 0
	global_load_lds_dwordx4 v246, s[96:97]
	s_add_u32 m0, s86, 0x5000
	s_nop 0
	global_load_lds_dwordx4 v247, s[88:89]
	s_add_u32 m0, s86, 0x2000
	s_nop 0
	global_load_lds_dwordx4 v248, s[96:97]
	s_add_u32 m0, s86, 0x6000
	s_nop 0
	global_load_lds_dwordx4 v249, s[88:89]
	s_add_u32 m0, s86, 0x3000
	s_nop 0
	global_load_lds_dwordx4 v250, s[96:97]
	s_add_u32 m0, s86, 0x7000
	s_nop 0
	global_load_lds_dwordx4 v251, s[88:89]
	s_add_u32 s96, s96, 0x80
	s_addc_u32 s97, s97, 0
	s_add_u32 s88, s88, 0x80
	s_addc_u32 s89, s89, 0
	s_and_b32 s43, s43, 0x8000
	s_add_i32 s43, s43, 0
	v_add3_u32 v212, s43, v88, v89
	v_add3_u32 v213, s43, v89, v90
	v_add3_u32 v214, s43, v88, v91
	v_add3_u32 v215, s43, v90, v91
	ds_read_b128 v[106:109], v213
	ds_read_b128 v[76:79], v212 offset:16384
	ds_read_b128 v[102:105], v212 offset:18432
	ds_read_b128 v[110:113], v213 offset:2048
	ds_read_b128 v[114:117], v212 offset:20480
	ds_read_b128 v[118:121], v212 offset:22528
	ds_read_b128 v[122:125], v212 offset:24576
	ds_read_b128 v[126:129], v212 offset:26624
	ds_read_b128 v[130:133], v212 offset:28672
	ds_read_b128 v[134:137], v212 offset:30720
	ds_read_b128 v[180:183], v215
	ds_read_b128 v[172:175], v214 offset:16384
	ds_read_b128 v[176:179], v214 offset:18432
	ds_read_b128 v[184:187], v215 offset:2048
	ds_read_b128 v[188:191], v214 offset:20480
	ds_read_b128 v[192:195], v214 offset:22528
	ds_read_b128 v[196:199], v214 offset:24576
	ds_read_b128 v[200:203], v214 offset:26624
	ds_read_b128 v[204:207], v214 offset:28672
	ds_read_b128 v[208:211], v214 offset:30720
	s_add_u32 s34, s34, 0x80
	s_addc_u32 s35, s35, 0
	s_cmpk_eq_i32 s34, 0x780
	s_mov_b32 s43, s45
	s_waitcnt lgkmcnt(15)
	v_mfma_f32_16x16x32_bf16 v[60:63], v[76:79], v[106:109], v[60:63]
	v_mfma_f32_16x16x32_bf16 v[56:59], v[102:105], v[106:109], v[56:59]
	v_mfma_f32_16x16x32_bf16 v[52:55], v[114:117], v[106:109], v[52:55]
	s_waitcnt lgkmcnt(14)
	v_mfma_f32_16x16x32_bf16 v[48:51], v[118:121], v[106:109], v[48:51]
	s_waitcnt lgkmcnt(13)
	v_mfma_f32_16x16x32_bf16 v[44:47], v[122:125], v[106:109], v[44:47]
	s_waitcnt lgkmcnt(12)
	v_mfma_f32_16x16x32_bf16 v[40:43], v[126:129], v[106:109], v[40:43]
	s_waitcnt lgkmcnt(11)
	v_mfma_f32_16x16x32_bf16 v[32:35], v[130:133], v[106:109], v[32:35]
	s_waitcnt lgkmcnt(10)
	v_mfma_f32_16x16x32_bf16 v[28:31], v[134:137], v[106:109], v[28:31]
	v_mfma_f32_16x16x32_bf16 v[24:27], v[76:79], v[110:113], v[24:27]
	v_mfma_f32_16x16x32_bf16 v[20:23], v[102:105], v[110:113], v[20:23]
	v_mfma_f32_16x16x32_bf16 v[16:19], v[114:117], v[110:113], v[16:19]
	v_mfma_f32_16x16x32_bf16 v[12:15], v[118:121], v[110:113], v[12:15]
	v_mfma_f32_16x16x32_bf16 v[8:11], v[122:125], v[110:113], v[8:11]
	v_mfma_f32_16x16x32_bf16 v[4:7], v[126:129], v[110:113], v[4:7]
	v_mfma_f32_16x16x32_bf16 v[0:3], v[130:133], v[110:113], v[0:3]
	v_mfma_f32_16x16x32_bf16 v[36:39], v[134:137], v[110:113], v[36:39]
	s_waitcnt lgkmcnt(8)
	v_mfma_f32_16x16x32_bf16 v[60:63], v[172:175], v[180:183], v[60:63]
	s_waitcnt lgkmcnt(7)
	v_mfma_f32_16x16x32_bf16 v[56:59], v[176:179], v[180:183], v[56:59]
	s_waitcnt lgkmcnt(5)
	v_mfma_f32_16x16x32_bf16 v[52:55], v[188:191], v[180:183], v[52:55]
	s_waitcnt lgkmcnt(4)
	v_mfma_f32_16x16x32_bf16 v[48:51], v[192:195], v[180:183], v[48:51]
	s_waitcnt lgkmcnt(3)
	v_mfma_f32_16x16x32_bf16 v[44:47], v[196:199], v[180:183], v[44:47]
	s_waitcnt lgkmcnt(2)
	v_mfma_f32_16x16x32_bf16 v[40:43], v[200:203], v[180:183], v[40:43]
	s_waitcnt lgkmcnt(1)
	v_mfma_f32_16x16x32_bf16 v[32:35], v[204:207], v[180:183], v[32:35]
	s_waitcnt lgkmcnt(0)
	v_mfma_f32_16x16x32_bf16 v[28:31], v[208:211], v[180:183], v[28:31]
	v_mfma_f32_16x16x32_bf16 v[24:27], v[172:175], v[184:187], v[24:27]
	v_mfma_f32_16x16x32_bf16 v[20:23], v[176:179], v[184:187], v[20:23]
	v_mfma_f32_16x16x32_bf16 v[16:19], v[188:191], v[184:187], v[16:19]
	v_mfma_f32_16x16x32_bf16 v[12:15], v[192:195], v[184:187], v[12:15]
	v_mfma_f32_16x16x32_bf16 v[8:11], v[196:199], v[184:187], v[8:11]
	v_mfma_f32_16x16x32_bf16 v[4:7], v[200:203], v[184:187], v[4:7]
	v_mfma_f32_16x16x32_bf16 v[0:3], v[204:207], v[184:187], v[0:3]
	v_mfma_f32_16x16x32_bf16 v[36:39], v[208:211], v[184:187], v[36:39]
	s_cbranch_scc0 .LBB0_855
	v_add_u32_e32 v80, s44, v88
	v_add_u32_e32 v81, v80, v89
	v_add3_u32 v106, s44, v89, v90
	s_waitcnt vmcnt(0)
	s_barrier
	ds_read_b128 v[72:75], v81 offset:16384
	ds_read_b128 v[76:79], v81 offset:18432
	ds_read_b128 v[102:105], v106
	ds_read_b128 v[106:109], v106 offset:2048
	ds_read_b128 v[110:113], v81 offset:20480
	ds_read_b128 v[114:117], v81 offset:22528
	ds_read_b128 v[118:121], v81 offset:24576
	ds_read_b128 v[122:125], v81 offset:26624
	ds_read_b128 v[126:129], v81 offset:28672
	ds_read_b128 v[130:133], v81 offset:30720
	v_add_u32_e32 v80, v80, v91
	s_waitcnt lgkmcnt(7)
	v_mfma_f32_16x16x32_bf16 v[60:63], v[72:75], v[102:105], v[60:63]
	s_lshl_b32 s42, s42, 7
	v_mfma_f32_16x16x32_bf16 v[56:59], v[76:79], v[102:105], v[56:59]
	s_waitcnt lgkmcnt(4)
	v_mfma_f32_16x16x32_bf16 v[48:51], v[114:117], v[102:105], v[48:51]
	s_waitcnt lgkmcnt(3)
	v_mfma_f32_16x16x32_bf16 v[44:47], v[118:121], v[102:105], v[44:47]
	s_waitcnt lgkmcnt(2)
	v_mfma_f32_16x16x32_bf16 v[40:43], v[122:125], v[102:105], v[40:43]
	s_waitcnt lgkmcnt(1)
	v_mfma_f32_16x16x32_bf16 v[32:35], v[126:129], v[102:105], v[32:35]
	s_waitcnt lgkmcnt(0)
	v_mfma_f32_16x16x32_bf16 v[28:31], v[130:133], v[102:105], v[28:31]
	v_mfma_f32_16x16x32_bf16 v[24:27], v[72:75], v[106:109], v[24:27]
	ds_read_b128 v[72:75], v80 offset:16384
	v_mfma_f32_16x16x32_bf16 v[52:55], v[110:113], v[102:105], v[52:55]
	v_mfma_f32_16x16x32_bf16 v[20:23], v[76:79], v[106:109], v[20:23]
	v_mfma_f32_16x16x32_bf16 v[16:19], v[110:113], v[106:109], v[16:19]
	v_mfma_f32_16x16x32_bf16 v[12:15], v[114:117], v[106:109], v[12:15]
	v_mfma_f32_16x16x32_bf16 v[8:11], v[118:121], v[106:109], v[8:11]
	v_mfma_f32_16x16x32_bf16 v[4:7], v[122:125], v[106:109], v[4:7]
	v_mfma_f32_16x16x32_bf16 v[0:3], v[126:129], v[106:109], v[0:3]
	v_mfma_f32_16x16x32_bf16 v[102:105], v[130:133], v[106:109], v[36:39]
	s_nop 2
	v_add3_u32 v36, s44, v91, v90
	ds_read_b128 v[76:79], v80 offset:18432
	ds_read_b128 v[106:109], v36
	ds_read_b128 v[110:113], v36 offset:2048
	ds_read_b128 v[130:133], v80 offset:28672
	ds_read_b128 v[134:137], v80 offset:30720
	ds_read_b128 v[114:117], v80 offset:20480
	ds_read_b128 v[118:121], v80 offset:22528
	ds_read_b128 v[122:125], v80 offset:24576
	ds_read_b128 v[126:129], v80 offset:26624
	s_waitcnt lgkmcnt(7)
	v_mfma_f32_16x16x32_bf16 v[60:63], v[72:75], v[106:109], v[60:63]
	v_readlane_b32 s44, v252, 5
	v_readlane_b32 s48, v252, 9
	v_readlane_b32 s49, v252, 10
	s_waitcnt lgkmcnt(5)
	v_mfma_f32_16x16x32_bf16 v[36:39], v[130:133], v[106:109], v[32:35]
	v_readlane_b32 s45, v252, 6
	v_readlane_b32 s46, v252, 7
	v_readlane_b32 s47, v252, 8
	s_waitcnt lgkmcnt(4)
	v_mfma_f32_16x16x32_bf16 v[32:35], v[134:137], v[106:109], v[28:31]
	v_readlane_b32 s50, v252, 11
	v_readlane_b32 s51, v252, 12
	v_readlane_b32 s52, v252, 13
	v_mfma_f32_16x16x32_bf16 v[28:31], v[72:75], v[110:113], v[24:27]
	v_add_u32_e32 v72, s42, v82
	v_mul_hi_i32 v73, v72, s36
	v_lshrrev_b32_e32 v74, 31, v73
	v_mfma_f32_16x16x32_bf16 v[24:27], v[76:79], v[110:113], v[20:23]
	v_readlane_b32 s53, v252, 14
	v_readlane_b32 s54, v252, 15
	v_readlane_b32 s55, v252, 16
	s_waitcnt lgkmcnt(3)
	v_mfma_f32_16x16x32_bf16 v[20:23], v[114:117], v[110:113], v[16:19]
	v_readlane_b32 s56, v252, 17
	v_readlane_b32 s57, v252, 18
	v_readlane_b32 s58, v252, 19
	s_waitcnt lgkmcnt(2)
	v_mfma_f32_16x16x32_bf16 v[16:19], v[118:121], v[110:113], v[12:15]
	v_readlane_b32 s59, v252, 20
	s_waitcnt lgkmcnt(1)
	v_mfma_f32_16x16x32_bf16 v[12:15], v[122:125], v[110:113], v[8:11]
	s_waitcnt lgkmcnt(0)
	v_mfma_f32_16x16x32_bf16 v[8:11], v[126:129], v[110:113], v[4:7]
	s_nop 2
	v_ashrrev_i32_e32 v4, 11, v73
	v_mfma_f32_16x16x32_bf16 v[56:59], v[76:79], v[106:109], v[56:59]
	v_add_u32_e32 v73, v4, v74
	v_mad_i32_i24 v75, v73, s37, v72
	v_lshlrev_b32_e32 v78, 13, v73
	v_mfma_f32_16x16x32_bf16 v[52:55], v[114:117], v[106:109], v[52:55]
	v_cmp_lt_i32_e32 vcc, s38, v75
	v_mov_b64_e32 v[76:77], s[48:49]
	v_add3_u32 v74, v78, v75, s39
	v_mfma_f32_16x16x32_bf16 v[48:51], v[118:121], v[106:109], v[48:51]
	v_mfma_f32_16x16x32_bf16 v[44:47], v[122:125], v[106:109], v[44:47]
	v_mfma_f32_16x16x32_bf16 v[40:43], v[126:129], v[106:109], v[40:43]
	v_mfma_f32_16x16x32_bf16 v[0:3], v[130:133], v[110:113], v[0:3]
	v_mfma_f32_16x16x32_bf16 v[4:7], v[134:137], v[110:113], v[102:105]
	s_and_saveexec_b64 s[34:35], vcc
	s_xor_b64 s[34:35], exec, s[34:35]
	s_cbranch_execz .LBB0_858
	v_readlane_b32 s44, v252, 5
	v_readlane_b32 s45, v252, 6
	v_add3_u32 v72, v78, v75, s39
	v_readlane_b32 s46, v252, 7
	v_readlane_b32 s47, v252, 8
	v_readlane_b32 s48, v252, 9
	v_readlane_b32 s49, v252, 10
	v_readlane_b32 s50, v252, 11
	v_readlane_b32 s51, v252, 12
	v_readlane_b32 s52, v252, 13
	v_readlane_b32 s53, v252, 14
	v_readlane_b32 s54, v252, 15
	v_readlane_b32 s55, v252, 16
	v_readlane_b32 s56, v252, 17
	v_readlane_b32 s57, v252, 18
	v_readlane_b32 s58, v252, 19
	v_readlane_b32 s59, v252, 20
	v_mov_b64_e32 v[76:77], s[44:45]
	s_or_saveexec_b64 s[34:35], s[34:35]
	v_lshl_add_u32 v102, v73, 8, v75
	s_xor_b64 exec, exec, s[34:35]
	s_branch .LBB0_859

.LBB0_1006:
	s_add_i32 s37, s35, 0x8000
	s_and_b32 s36, s37, 0x8000
	s_add_i32 s36, s36, 0
	s_add_u32 s86, s36, s87
	s_mov_b32 m0, s86
	s_waitcnt vmcnt(0) lgkmcnt(0)
	s_barrier
	global_load_lds_dwordx4 v244, s[96:97]
	s_add_u32 m0, s86, 0x4000
	s_nop 0
	global_load_lds_dwordx4 v245, s[88:89]
	s_add_u32 m0, s86, 0x1000
	s_nop 0
	global_load_lds_dwordx4 v246, s[96:97]
	s_add_u32 m0, s86, 0x5000
	s_nop 0
	global_load_lds_dwordx4 v247, s[88:89]
	s_add_u32 m0, s86, 0x2000
	s_nop 0
	global_load_lds_dwordx4 v248, s[96:97]
	s_add_u32 m0, s86, 0x6000
	s_nop 0
	global_load_lds_dwordx4 v249, s[88:89]
	s_add_u32 m0, s86, 0x3000
	s_nop 0
	global_load_lds_dwordx4 v250, s[96:97]
	s_add_u32 m0, s86, 0x7000
	s_nop 0
	global_load_lds_dwordx4 v251, s[88:89]
	s_add_u32 s96, s96, 0x80
	s_addc_u32 s97, s97, 0
	s_add_u32 s88, s88, 0x80
	s_addc_u32 s89, s89, 0
	s_and_b32 s35, s35, 0x8000
	s_add_i32 s35, s35, 0
	v_add3_u32 v143, s35, v80, v81
	v_add3_u32 v145, s35, v81, v82
	v_add3_u32 v206, s35, v80, v83
	v_add3_u32 v207, s35, v82, v83
	ds_read_b128 v[102:105], v145
	ds_read_b128 v[94:97], v143 offset:16384
	ds_read_b128 v[98:101], v143 offset:18432
	ds_read_b128 v[106:109], v145 offset:2048
	ds_read_b128 v[110:113], v143 offset:20480
	ds_read_b128 v[114:117], v143 offset:22528
	ds_read_b128 v[118:121], v143 offset:24576
	ds_read_b128 v[122:125], v143 offset:26624
	ds_read_b128 v[126:129], v143 offset:28672
	ds_read_b128 v[130:133], v143 offset:30720
	ds_read_b128 v[174:177], v207
	ds_read_b128 v[166:169], v206 offset:16384
	ds_read_b128 v[170:173], v206 offset:18432
	ds_read_b128 v[178:181], v207 offset:2048
	ds_read_b128 v[182:185], v206 offset:20480
	ds_read_b128 v[186:189], v206 offset:22528
	ds_read_b128 v[190:193], v206 offset:24576
	ds_read_b128 v[194:197], v206 offset:26624
	ds_read_b128 v[198:201], v206 offset:28672
	ds_read_b128 v[202:205], v206 offset:30720
	s_add_u32 s26, s26, 0x80
	s_addc_u32 s27, s27, 0
	s_cmpk_eq_i32 s26, 0x780
	s_mov_b32 s35, s37
	s_waitcnt lgkmcnt(15)
	v_mfma_f32_16x16x32_bf16 v[60:63], v[94:97], v[102:105], v[60:63]
	v_mfma_f32_16x16x32_bf16 v[56:59], v[98:101], v[102:105], v[56:59]
	v_mfma_f32_16x16x32_bf16 v[52:55], v[110:113], v[102:105], v[52:55]
	s_waitcnt lgkmcnt(14)
	v_mfma_f32_16x16x32_bf16 v[48:51], v[114:117], v[102:105], v[48:51]
	s_waitcnt lgkmcnt(13)
	v_mfma_f32_16x16x32_bf16 v[44:47], v[118:121], v[102:105], v[44:47]
	s_waitcnt lgkmcnt(12)
	v_mfma_f32_16x16x32_bf16 v[40:43], v[122:125], v[102:105], v[40:43]
	s_waitcnt lgkmcnt(11)
	v_mfma_f32_16x16x32_bf16 v[36:39], v[126:129], v[102:105], v[36:39]
	s_waitcnt lgkmcnt(10)
	v_mfma_f32_16x16x32_bf16 v[32:35], v[130:133], v[102:105], v[32:35]
	v_mfma_f32_16x16x32_bf16 v[28:31], v[94:97], v[106:109], v[28:31]
	v_mfma_f32_16x16x32_bf16 v[24:27], v[98:101], v[106:109], v[24:27]
	v_mfma_f32_16x16x32_bf16 v[16:19], v[110:113], v[106:109], v[16:19]
	v_mfma_f32_16x16x32_bf16 v[12:15], v[114:117], v[106:109], v[12:15]
	v_mfma_f32_16x16x32_bf16 v[8:11], v[118:121], v[106:109], v[8:11]
	v_mfma_f32_16x16x32_bf16 v[4:7], v[122:125], v[106:109], v[4:7]
	v_mfma_f32_16x16x32_bf16 v[0:3], v[126:129], v[106:109], v[0:3]
	v_mfma_f32_16x16x32_bf16 v[20:23], v[130:133], v[106:109], v[20:23]
	s_waitcnt lgkmcnt(8)
	v_mfma_f32_16x16x32_bf16 v[60:63], v[166:169], v[174:177], v[60:63]
	s_waitcnt lgkmcnt(7)
	v_mfma_f32_16x16x32_bf16 v[56:59], v[170:173], v[174:177], v[56:59]
	s_waitcnt lgkmcnt(5)
	v_mfma_f32_16x16x32_bf16 v[52:55], v[182:185], v[174:177], v[52:55]
	s_waitcnt lgkmcnt(4)
	v_mfma_f32_16x16x32_bf16 v[48:51], v[186:189], v[174:177], v[48:51]
	s_waitcnt lgkmcnt(3)
	v_mfma_f32_16x16x32_bf16 v[44:47], v[190:193], v[174:177], v[44:47]
	s_waitcnt lgkmcnt(2)
	v_mfma_f32_16x16x32_bf16 v[40:43], v[194:197], v[174:177], v[40:43]
	s_waitcnt lgkmcnt(1)
	v_mfma_f32_16x16x32_bf16 v[36:39], v[198:201], v[174:177], v[36:39]
	s_waitcnt lgkmcnt(0)
	v_mfma_f32_16x16x32_bf16 v[32:35], v[202:205], v[174:177], v[32:35]
	v_mfma_f32_16x16x32_bf16 v[28:31], v[166:169], v[178:181], v[28:31]
	v_mfma_f32_16x16x32_bf16 v[24:27], v[170:173], v[178:181], v[24:27]
	v_mfma_f32_16x16x32_bf16 v[16:19], v[182:185], v[178:181], v[16:19]
	v_mfma_f32_16x16x32_bf16 v[12:15], v[186:189], v[178:181], v[12:15]
	v_mfma_f32_16x16x32_bf16 v[8:11], v[190:193], v[178:181], v[8:11]
	v_mfma_f32_16x16x32_bf16 v[4:7], v[194:197], v[178:181], v[4:7]
	v_mfma_f32_16x16x32_bf16 v[0:3], v[198:201], v[178:181], v[0:3]
	v_mfma_f32_16x16x32_bf16 v[20:23], v[202:205], v[178:181], v[20:23]
	s_cbranch_scc0 .LBB0_1006
	v_add_u32_e32 v138, s36, v80
	v_add_u32_e32 v126, v138, v81
	s_waitcnt vmcnt(0)
	s_barrier
	ds_read_b128 v[74:77], v126 offset:16384
	v_add3_u32 v102, s36, v81, v82
	ds_read_b128 v[94:97], v102
	ds_read_b128 v[98:101], v126 offset:18432
	ds_read_b128 v[102:105], v102 offset:2048
	ds_read_b128 v[106:109], v126 offset:20480
	ds_read_b128 v[110:113], v126 offset:22528
	ds_read_b128 v[114:117], v126 offset:24576
	ds_read_b128 v[118:121], v126 offset:26624
	v_add3_u32 v134, s36, v83, v82
	v_add_u32_e32 v142, v138, v83
	ds_read_b128 v[122:125], v126 offset:28672
	ds_read_b128 v[126:129], v126 offset:30720
	ds_read_b128 v[130:133], v134
	ds_read_b128 v[134:137], v134 offset:2048
	ds_read_b128 v[138:141], v142 offset:16384
	ds_read_b128 v[146:149], v142 offset:18432
	s_waitcnt lgkmcnt(11)
	v_mfma_f32_16x16x32_bf16 v[56:59], v[98:101], v[94:97], v[56:59]
	s_lshl_b32 s36, s34, 7
	s_lshl_b32 s26, s33, 7
	s_ashr_i32 s27, s26, 31
	v_mfma_f32_16x16x32_bf16 v[60:63], v[74:77], v[94:97], v[60:63]
	s_lshl_b64 s[26:27], s[26:27], 1
	s_add_i32 s31, s31, s28
	s_cmpk_gt_i32 s31, 0x107f
	s_waitcnt lgkmcnt(0)
	v_mfma_f32_16x16x32_bf16 v[56:59], v[146:149], v[130:133], v[56:59]
	v_mfma_f32_16x16x32_bf16 v[48:51], v[110:113], v[94:97], v[48:51]
	v_mfma_f32_16x16x32_bf16 v[52:55], v[106:109], v[94:97], v[52:55]
	s_nop 5
	v_max_f32_e32 v56, v56, v56
	v_max_f32_e32 v57, v57, v57
	v_max_f32_e32 v56, 0, v56
	v_mfma_f32_16x16x32_bf16 v[44:47], v[114:117], v[94:97], v[44:47]
	v_max_f32_e32 v57, 0, v57
	v_max_f32_e32 v59, v59, v59
	v_max_f32_e32 v59, 0, v59
	v_mfma_f32_16x16x32_bf16 v[40:43], v[118:121], v[94:97], v[40:43]
	v_mfma_f32_16x16x32_bf16 v[36:39], v[122:125], v[94:97], v[36:39]
	v_mfma_f32_16x16x32_bf16 v[32:35], v[126:129], v[94:97], v[32:35]
	ds_read_b128 v[94:97], v142 offset:20480
	ds_read_b128 v[150:153], v142 offset:22528
	ds_read_b128 v[154:157], v142 offset:24576
	ds_read_b128 v[158:161], v142 offset:26624
	v_mfma_f32_16x16x32_bf16 v[60:63], v[138:141], v[130:133], v[60:63]
	s_waitcnt lgkmcnt(2)
	v_mfma_f32_16x16x32_bf16 v[48:51], v[150:153], v[130:133], v[48:51]
	v_mfma_f32_16x16x32_bf16 v[16:19], v[106:109], v[102:105], v[16:19]
	v_mul_f32_e64 v106, v56, v56
	v_mul_f32_e64 v107, v57, v57
	v_max_f32_e32 v57, v58, v58
	s_nop 1
	v_max_f32_e32 v60, v60, v60
	v_mfma_f32_16x16x32_bf16 v[24:27], v[98:101], v[102:105], v[24:27]
	v_add_u32_e32 v100, s36, v79
	v_mov_b64_e32 v[98:99], s[0:1]
	v_max_f32_e32 v61, v61, v61
	v_max_f32_e32 v56, v62, v62
	v_max_f32_e32 v58, 0, v57
	v_max_f32_e32 v57, v63, v63
	v_mad_i64_i32 v[100:101], s[34:35], v100, s30, v[98:99]
	v_max_f32_e32 v60, 0, v60
	v_max_f32_e32 v61, 0, v61
	v_max_f32_e32 v56, 0, v56
	v_max_f32_e32 v57, 0, v57
	v_mfma_f32_16x16x32_bf16 v[52:55], v[94:97], v[130:133], v[52:55]
	v_lshl_add_u64 v[100:101], v[100:101], 0, s[26:27]
	v_pk_mul_f32 v[60:61], v[60:61], v[60:61]
	v_pk_mul_f32 v[62:63], v[56:57], v[56:57]
	v_mfma_f32_16x16x32_bf16 v[28:31], v[74:77], v[102:105], v[28:31]
	v_max_f32_e32 v48, v48, v48
	v_max_f32_e32 v49, v49, v49
	ds_read_b128 v[74:77], v142 offset:28672
	ds_read_b128 v[162:165], v142 offset:30720
	v_mfma_f32_16x16x32_bf16 v[12:15], v[110:113], v[102:105], v[12:15]
	v_lshl_add_u64 v[100:101], v[100:101], 0, v[64:65]
	v_cvt_pk_bf16_f32 v56, v60, v61
	v_cvt_pk_bf16_f32 v57, v62, v63
	v_mfma_f32_16x16x32_bf16 v[8:11], v[114:117], v[102:105], v[8:11]
	v_max_f32_e32 v48, 0, v48
	v_max_f32_e32 v49, 0, v49
	v_max_f32_e32 v52, v52, v52
	v_mfma_f32_16x16x32_bf16 v[4:7], v[118:121], v[102:105], v[4:7]
	v_max_f32_e32 v53, v53, v53
	v_max_f32_e32 v51, v51, v51
	v_max_f32_e32 v52, 0, v52
	v_mfma_f32_16x16x32_bf16 v[0:3], v[122:125], v[102:105], v[0:3]
	v_max_f32_e32 v53, 0, v53
	v_max_f32_e32 v51, 0, v51
	v_pk_mul_f32 v[52:53], v[52:53], v[52:53]
	v_mfma_f32_16x16x32_bf16 v[20:23], v[126:129], v[102:105], v[20:23]
	v_mul_f32_e64 v102, v58, v58
	v_mul_f32_e64 v103, v59, v59
	v_cvt_pk_bf16_f32 v58, v106, v107
	v_cvt_pk_bf16_f32 v59, v102, v103
	s_waitcnt lgkmcnt(2)
	v_mfma_f32_16x16x32_bf16 v[40:43], v[158:161], v[130:133], v[40:43]
	global_store_dwordx4 v[100:101], v[56:59], off
	s_nop 1
	v_pk_mul_f32 v[56:57], v[48:49], v[48:49]
	v_max_f32_e32 v49, v50, v50
	v_max_f32_e32 v48, v54, v54
	v_max_f32_e32 v50, 0, v49
	v_max_f32_e32 v49, v55, v55
	v_mfma_f32_16x16x32_bf16 v[44:47], v[154:157], v[130:133], v[44:47]
	v_max_f32_e32 v48, 0, v48
	v_max_f32_e32 v49, 0, v49
	v_pk_mul_f32 v[54:55], v[48:49], v[48:49]
	v_pk_mul_f32 v[58:59], v[50:51], v[50:51]
	v_max_f32_e32 v40, v40, v40
	v_max_f32_e32 v41, v41, v41
	s_waitcnt lgkmcnt(0)
	v_mfma_f32_16x16x32_bf16 v[32:35], v[162:165], v[130:133], v[32:35]
	v_cvt_pk_bf16_f32 v48, v52, v53
	v_cvt_pk_bf16_f32 v49, v54, v55
	v_cvt_pk_bf16_f32 v50, v56, v57
	v_cvt_pk_bf16_f32 v51, v58, v59
	v_max_f32_e32 v40, 0, v40
	v_max_f32_e32 v41, 0, v41
	global_store_dwordx4 v[100:101], v[48:51], off offset:64
	v_max_f32_e32 v44, v44, v44
	v_max_f32_e32 v45, v45, v45
	v_pk_mul_f32 v[48:49], v[40:41], v[40:41]
	v_max_f32_e32 v41, v42, v42
	v_max_f32_e32 v40, v46, v46
	v_max_f32_e32 v42, 0, v41
	v_max_f32_e32 v41, v47, v47
	v_max_f32_e32 v43, v43, v43
	v_mfma_f32_16x16x32_bf16 v[36:39], v[74:77], v[130:133], v[36:39]
	v_max_f32_e32 v44, 0, v44
	v_max_f32_e32 v45, 0, v45
	v_max_f32_e32 v40, 0, v40
	v_max_f32_e32 v41, 0, v41
	v_max_f32_e32 v43, 0, v43
	v_pk_mul_f32 v[44:45], v[44:45], v[44:45]
	v_pk_mul_f32 v[46:47], v[40:41], v[40:41]
	v_pk_mul_f32 v[50:51], v[42:43], v[42:43]
	v_max_f32_e32 v32, v32, v32
	v_max_f32_e32 v33, v33, v33
	v_mfma_f32_16x16x32_bf16 v[24:27], v[146:149], v[134:137], v[24:27]
	v_cvt_pk_bf16_f32 v40, v44, v45
	v_cvt_pk_bf16_f32 v41, v46, v47
	v_cvt_pk_bf16_f32 v42, v48, v49
	v_cvt_pk_bf16_f32 v43, v50, v51
	v_max_f32_e32 v32, 0, v32
	v_max_f32_e32 v33, 0, v33
	global_store_dwordx4 v[100:101], v[40:43], off offset:128
	v_max_f32_e32 v36, v36, v36
	v_max_f32_e32 v37, v37, v37
	v_pk_mul_f32 v[40:41], v[32:33], v[32:33]
	v_max_f32_e32 v33, v34, v34
	v_max_f32_e32 v32, v38, v38
	v_max_f32_e32 v34, 0, v33
	v_max_f32_e32 v33, v39, v39
	v_max_f32_e32 v35, v35, v35
	v_mfma_f32_16x16x32_bf16 v[28:31], v[138:141], v[134:137], v[28:31]
	v_max_f32_e32 v36, 0, v36
	v_max_f32_e32 v37, 0, v37
	v_max_f32_e32 v32, 0, v32
	v_max_f32_e32 v33, 0, v33
	v_max_f32_e32 v35, 0, v35
	v_pk_mul_f32 v[36:37], v[36:37], v[36:37]
	v_pk_mul_f32 v[38:39], v[32:33], v[32:33]
	v_pk_mul_f32 v[42:43], v[34:35], v[34:35]
	v_max_f32_e32 v24, v24, v24
	v_max_f32_e32 v25, v25, v25
	v_mfma_f32_16x16x32_bf16 v[12:15], v[150:153], v[134:137], v[12:15]
	v_cvt_pk_bf16_f32 v32, v36, v37
	v_cvt_pk_bf16_f32 v33, v38, v39
	v_cvt_pk_bf16_f32 v34, v40, v41
	v_cvt_pk_bf16_f32 v35, v42, v43
	v_max_f32_e32 v24, 0, v24
	v_max_f32_e32 v25, 0, v25
	global_store_dwordx4 v[100:101], v[32:35], off offset:192
	v_max_f32_e32 v28, v28, v28
	v_max_f32_e32 v29, v29, v29
	v_pk_mul_f32 v[34:35], v[24:25], v[24:25]
	v_max_f32_e32 v25, v26, v26
	v_add_u32_e32 v32, s36, v84
	v_max_f32_e32 v24, v30, v30
	v_max_f32_e32 v26, 0, v25
	v_max_f32_e32 v25, v31, v31
	v_max_f32_e32 v27, v27, v27
	v_mfma_f32_16x16x32_bf16 v[16:19], v[94:97], v[134:137], v[16:19]
	v_mad_i64_i32 v[32:33], s[34:35], v32, s30, v[98:99]
	v_max_f32_e32 v28, 0, v28
	v_max_f32_e32 v29, 0, v29
	v_max_f32_e32 v24, 0, v24
	v_max_f32_e32 v25, 0, v25
	v_max_f32_e32 v27, 0, v27
	v_lshl_add_u64 v[32:33], v[32:33], 0, s[26:27]
	v_pk_mul_f32 v[28:29], v[28:29], v[28:29]
	v_pk_mul_f32 v[30:31], v[24:25], v[24:25]
	v_pk_mul_f32 v[36:37], v[26:27], v[26:27]
	v_max_f32_e32 v12, v12, v12
	v_max_f32_e32 v13, v13, v13
	v_mfma_f32_16x16x32_bf16 v[4:7], v[158:161], v[134:137], v[4:7]
	v_lshl_add_u64 v[32:33], v[32:33], 0, v[64:65]
	v_cvt_pk_bf16_f32 v24, v28, v29
	v_cvt_pk_bf16_f32 v25, v30, v31
	v_cvt_pk_bf16_f32 v26, v34, v35
	v_cvt_pk_bf16_f32 v27, v36, v37
	v_max_f32_e32 v12, 0, v12
	v_max_f32_e32 v13, 0, v13
	global_store_dwordx4 v[32:33], v[24:27], off
	v_max_f32_e32 v16, v16, v16
	v_max_f32_e32 v17, v17, v17
	v_pk_mul_f32 v[24:25], v[12:13], v[12:13]
	v_max_f32_e32 v13, v14, v14
	v_max_f32_e32 v12, v18, v18
	v_max_f32_e32 v14, 0, v13
	v_max_f32_e32 v13, v19, v19
	v_max_f32_e32 v15, v15, v15
	v_mfma_f32_16x16x32_bf16 v[8:11], v[154:157], v[134:137], v[8:11]
	v_max_f32_e32 v16, 0, v16
	v_max_f32_e32 v17, 0, v17
	v_max_f32_e32 v12, 0, v12
	v_max_f32_e32 v13, 0, v13
	v_max_f32_e32 v15, 0, v15
	v_pk_mul_f32 v[16:17], v[16:17], v[16:17]
	v_pk_mul_f32 v[18:19], v[12:13], v[12:13]
	v_pk_mul_f32 v[26:27], v[14:15], v[14:15]
	v_max_f32_e32 v4, v4, v4
	v_max_f32_e32 v5, v5, v5
	v_cvt_pk_bf16_f32 v12, v16, v17
	v_cvt_pk_bf16_f32 v13, v18, v19
	v_cvt_pk_bf16_f32 v14, v24, v25
	v_cvt_pk_bf16_f32 v15, v26, v27
	v_max_f32_e32 v4, 0, v4
	v_max_f32_e32 v5, 0, v5
	global_store_dwordx4 v[32:33], v[12:15], off offset:64
	v_mfma_f32_16x16x32_bf16 v[0:3], v[74:77], v[134:137], v[0:3]
	v_max_f32_e32 v8, v8, v8
	v_pk_mul_f32 v[12:13], v[4:5], v[4:5]
	v_max_f32_e32 v5, v6, v6
	v_mfma_f32_16x16x32_bf16 v[20:23], v[162:165], v[134:137], v[20:23]
	v_max_f32_e32 v9, v9, v9
	v_max_f32_e32 v4, v10, v10
	v_max_f32_e32 v6, 0, v5
	v_max_f32_e32 v5, v11, v11
	v_max_f32_e32 v7, v7, v7
	v_max_f32_e32 v8, 0, v8
	v_max_f32_e32 v9, 0, v9
	v_max_f32_e32 v4, 0, v4
	v_max_f32_e32 v5, 0, v5
	v_max_f32_e32 v7, 0, v7
	v_pk_mul_f32 v[8:9], v[8:9], v[8:9]
	v_pk_mul_f32 v[10:11], v[4:5], v[4:5]
	v_pk_mul_f32 v[14:15], v[6:7], v[6:7]
	v_cvt_pk_bf16_f32 v4, v8, v9
	v_cvt_pk_bf16_f32 v5, v10, v11
	v_cvt_pk_bf16_f32 v6, v12, v13
	v_cvt_pk_bf16_f32 v7, v14, v15
	global_store_dwordx4 v[32:33], v[4:7], off offset:128
	v_max_f32_e32 v0, v0, v0
	v_max_f32_e32 v1, v1, v1
	v_max_f32_e32 v4, v20, v20
	v_max_f32_e32 v5, v21, v21
	v_max_f32_e32 v2, v2, v2
	v_max_f32_e32 v6, v22, v22
	v_max_f32_e32 v3, v3, v3
	v_max_f32_e32 v7, v23, v23
	v_max_f32_e32 v0, 0, v0
	v_max_f32_e32 v4, 0, v4
	v_max_f32_e32 v1, 0, v1
	v_max_f32_e32 v5, 0, v5
	v_max_f32_e32 v2, 0, v2
	v_max_f32_e32 v6, 0, v6
	v_max_f32_e32 v3, 0, v3
	v_max_f32_e32 v7, 0, v7
	v_pk_mul_f32 v[0:1], v[0:1], v[0:1]
	v_pk_mul_f32 v[4:5], v[4:5], v[4:5]
	v_pk_mul_f32 v[2:3], v[2:3], v[2:3]
	v_pk_mul_f32 v[6:7], v[6:7], v[6:7]
	v_cvt_pk_bf16_f32 v0, v0, v1
	v_cvt_pk_bf16_f32 v1, v2, v3
	v_cvt_pk_bf16_f32 v2, v4, v5
	v_cvt_pk_bf16_f32 v3, v6, v7
	global_store_dwordx4 v[32:33], v[0:3], off offset:192
	s_cbranch_scc0 .LBB0_1005

.LBB0_1071:
	s_add_i32 s45, s43, 0x8000
	s_and_b32 s44, s45, 0x8000
	s_add_i32 s44, s44, 0
	s_add_u32 s86, s44, s87
	s_mov_b32 m0, s86
	s_waitcnt vmcnt(0) lgkmcnt(0)
	s_barrier
	global_load_lds_dwordx4 v244, s[96:97]
	s_add_u32 m0, s86, 0x4000
	s_nop 0
	global_load_lds_dwordx4 v245, s[88:89]
	s_add_u32 m0, s86, 0x1000
	s_nop 0
	global_load_lds_dwordx4 v246, s[96:97]
	s_add_u32 m0, s86, 0x5000
	s_nop 0
	global_load_lds_dwordx4 v247, s[88:89]
	s_add_u32 m0, s86, 0x2000
	s_nop 0
	global_load_lds_dwordx4 v248, s[96:97]
	s_add_u32 m0, s86, 0x6000
	s_nop 0
	global_load_lds_dwordx4 v249, s[88:89]
	s_add_u32 m0, s86, 0x3000
	s_nop 0
	global_load_lds_dwordx4 v250, s[96:97]
	s_add_u32 m0, s86, 0x7000
	s_nop 0
	global_load_lds_dwordx4 v251, s[88:89]
	s_add_u32 s96, s96, 0x80
	s_addc_u32 s97, s97, 0
	s_add_u32 s88, s88, 0x80
	s_addc_u32 s89, s89, 0
	s_and_b32 s43, s43, 0x8000
	s_add_i32 s43, s43, 0
	v_add3_u32 v169, s43, v84, v89
	v_add3_u32 v210, s43, v89, v90
	v_add3_u32 v211, s43, v84, v91
	v_add3_u32 v212, s43, v90, v91
	ds_read_b128 v[106:109], v210
	ds_read_b128 v[76:79], v169 offset:16384
	ds_read_b128 v[102:105], v169 offset:18432
	ds_read_b128 v[110:113], v210 offset:2048
	ds_read_b128 v[114:117], v169 offset:20480
	ds_read_b128 v[118:121], v169 offset:22528
	ds_read_b128 v[122:125], v169 offset:24576
	ds_read_b128 v[126:129], v169 offset:26624
	ds_read_b128 v[130:133], v169 offset:28672
	ds_read_b128 v[134:137], v169 offset:30720
	ds_read_b128 v[178:181], v212
	ds_read_b128 v[170:173], v211 offset:16384
	ds_read_b128 v[174:177], v211 offset:18432
	ds_read_b128 v[182:185], v212 offset:2048
	ds_read_b128 v[186:189], v211 offset:20480
	ds_read_b128 v[190:193], v211 offset:22528
	ds_read_b128 v[194:197], v211 offset:24576
	ds_read_b128 v[198:201], v211 offset:26624
	ds_read_b128 v[202:205], v211 offset:28672
	ds_read_b128 v[206:209], v211 offset:30720
	s_add_u32 s34, s34, 0x80
	s_addc_u32 s35, s35, 0
	s_cmpk_eq_i32 s34, 0x1f80
	s_mov_b32 s43, s45
	s_waitcnt lgkmcnt(15)
	v_mfma_f32_16x16x32_bf16 v[60:63], v[76:79], v[106:109], v[60:63]
	v_mfma_f32_16x16x32_bf16 v[56:59], v[102:105], v[106:109], v[56:59]
	v_mfma_f32_16x16x32_bf16 v[52:55], v[114:117], v[106:109], v[52:55]
	s_waitcnt lgkmcnt(14)
	v_mfma_f32_16x16x32_bf16 v[48:51], v[118:121], v[106:109], v[48:51]
	s_waitcnt lgkmcnt(13)
	v_mfma_f32_16x16x32_bf16 v[44:47], v[122:125], v[106:109], v[44:47]
	s_waitcnt lgkmcnt(12)
	v_mfma_f32_16x16x32_bf16 v[40:43], v[126:129], v[106:109], v[40:43]
	s_waitcnt lgkmcnt(11)
	v_mfma_f32_16x16x32_bf16 v[32:35], v[130:133], v[106:109], v[32:35]
	s_waitcnt lgkmcnt(10)
	v_mfma_f32_16x16x32_bf16 v[28:31], v[134:137], v[106:109], v[28:31]
	v_mfma_f32_16x16x32_bf16 v[24:27], v[76:79], v[110:113], v[24:27]
	v_mfma_f32_16x16x32_bf16 v[20:23], v[102:105], v[110:113], v[20:23]
	v_mfma_f32_16x16x32_bf16 v[16:19], v[114:117], v[110:113], v[16:19]
	v_mfma_f32_16x16x32_bf16 v[12:15], v[118:121], v[110:113], v[12:15]
	v_mfma_f32_16x16x32_bf16 v[8:11], v[122:125], v[110:113], v[8:11]
	v_mfma_f32_16x16x32_bf16 v[4:7], v[126:129], v[110:113], v[4:7]
	v_mfma_f32_16x16x32_bf16 v[0:3], v[130:133], v[110:113], v[0:3]
	v_mfma_f32_16x16x32_bf16 v[36:39], v[134:137], v[110:113], v[36:39]
	s_waitcnt lgkmcnt(8)
	v_mfma_f32_16x16x32_bf16 v[60:63], v[170:173], v[178:181], v[60:63]
	s_waitcnt lgkmcnt(7)
	v_mfma_f32_16x16x32_bf16 v[56:59], v[174:177], v[178:181], v[56:59]
	s_waitcnt lgkmcnt(5)
	v_mfma_f32_16x16x32_bf16 v[52:55], v[186:189], v[178:181], v[52:55]
	s_waitcnt lgkmcnt(4)
	v_mfma_f32_16x16x32_bf16 v[48:51], v[190:193], v[178:181], v[48:51]
	s_waitcnt lgkmcnt(3)
	v_mfma_f32_16x16x32_bf16 v[44:47], v[194:197], v[178:181], v[44:47]
	s_waitcnt lgkmcnt(2)
	v_mfma_f32_16x16x32_bf16 v[40:43], v[198:201], v[178:181], v[40:43]
	s_waitcnt lgkmcnt(1)
	v_mfma_f32_16x16x32_bf16 v[32:35], v[202:205], v[178:181], v[32:35]
	s_waitcnt lgkmcnt(0)
	v_mfma_f32_16x16x32_bf16 v[28:31], v[206:209], v[178:181], v[28:31]
	v_mfma_f32_16x16x32_bf16 v[24:27], v[170:173], v[182:185], v[24:27]
	v_mfma_f32_16x16x32_bf16 v[20:23], v[174:177], v[182:185], v[20:23]
	v_mfma_f32_16x16x32_bf16 v[16:19], v[186:189], v[182:185], v[16:19]
	v_mfma_f32_16x16x32_bf16 v[12:15], v[190:193], v[182:185], v[12:15]
	v_mfma_f32_16x16x32_bf16 v[8:11], v[194:197], v[182:185], v[8:11]
	v_mfma_f32_16x16x32_bf16 v[4:7], v[198:201], v[182:185], v[4:7]
	v_mfma_f32_16x16x32_bf16 v[0:3], v[202:205], v[182:185], v[0:3]
	v_mfma_f32_16x16x32_bf16 v[36:39], v[206:209], v[182:185], v[36:39]
	s_cbranch_scc0 .LBB0_1071
	v_add_u32_e32 v80, s44, v84
	v_add_u32_e32 v81, v80, v89
	v_add3_u32 v106, s44, v89, v90
	s_waitcnt vmcnt(0)
	s_barrier
	ds_read_b128 v[72:75], v81 offset:16384
	ds_read_b128 v[76:79], v81 offset:18432
	ds_read_b128 v[102:105], v106
	ds_read_b128 v[106:109], v106 offset:2048
	ds_read_b128 v[110:113], v81 offset:20480
	ds_read_b128 v[114:117], v81 offset:22528
	ds_read_b128 v[118:121], v81 offset:24576
	ds_read_b128 v[122:125], v81 offset:26624
	ds_read_b128 v[126:129], v81 offset:28672
	ds_read_b128 v[130:133], v81 offset:30720
	v_add_u32_e32 v80, v80, v91
	s_waitcnt lgkmcnt(7)
	v_mfma_f32_16x16x32_bf16 v[60:63], v[72:75], v[102:105], v[60:63]
	s_lshl_b32 s42, s42, 7
	v_mfma_f32_16x16x32_bf16 v[56:59], v[76:79], v[102:105], v[56:59]
	s_waitcnt lgkmcnt(4)
	v_mfma_f32_16x16x32_bf16 v[48:51], v[114:117], v[102:105], v[48:51]
	s_waitcnt lgkmcnt(3)
	v_mfma_f32_16x16x32_bf16 v[44:47], v[118:121], v[102:105], v[44:47]
	s_waitcnt lgkmcnt(2)
	v_mfma_f32_16x16x32_bf16 v[40:43], v[122:125], v[102:105], v[40:43]
	s_waitcnt lgkmcnt(1)
	v_mfma_f32_16x16x32_bf16 v[32:35], v[126:129], v[102:105], v[32:35]
	s_waitcnt lgkmcnt(0)
	v_mfma_f32_16x16x32_bf16 v[28:31], v[130:133], v[102:105], v[28:31]
	v_mfma_f32_16x16x32_bf16 v[24:27], v[72:75], v[106:109], v[24:27]
	ds_read_b128 v[72:75], v80 offset:16384
	v_mfma_f32_16x16x32_bf16 v[52:55], v[110:113], v[102:105], v[52:55]
	v_mfma_f32_16x16x32_bf16 v[20:23], v[76:79], v[106:109], v[20:23]
	v_mfma_f32_16x16x32_bf16 v[16:19], v[110:113], v[106:109], v[16:19]
	v_mfma_f32_16x16x32_bf16 v[12:15], v[114:117], v[106:109], v[12:15]
	v_mfma_f32_16x16x32_bf16 v[8:11], v[118:121], v[106:109], v[8:11]
	v_mfma_f32_16x16x32_bf16 v[4:7], v[122:125], v[106:109], v[4:7]
	v_mfma_f32_16x16x32_bf16 v[0:3], v[126:129], v[106:109], v[0:3]
	v_mfma_f32_16x16x32_bf16 v[102:105], v[130:133], v[106:109], v[36:39]
	s_nop 2
	v_add3_u32 v36, s44, v91, v90
	ds_read_b128 v[76:79], v80 offset:18432
	ds_read_b128 v[106:109], v36
	ds_read_b128 v[110:113], v36 offset:2048
	ds_read_b128 v[130:133], v80 offset:28672
	ds_read_b128 v[134:137], v80 offset:30720
	ds_read_b128 v[114:117], v80 offset:20480
	ds_read_b128 v[118:121], v80 offset:22528
	ds_read_b128 v[122:125], v80 offset:24576
	ds_read_b128 v[126:129], v80 offset:26624
	s_waitcnt lgkmcnt(7)
	v_mfma_f32_16x16x32_bf16 v[60:63], v[72:75], v[106:109], v[60:63]
	s_waitcnt lgkmcnt(5)
	v_mfma_f32_16x16x32_bf16 v[36:39], v[130:133], v[106:109], v[32:35]
	s_waitcnt lgkmcnt(4)
	v_mfma_f32_16x16x32_bf16 v[32:35], v[134:137], v[106:109], v[28:31]
	v_mfma_f32_16x16x32_bf16 v[28:31], v[72:75], v[110:113], v[24:27]
	v_add_u32_e32 v72, s42, v85
	v_mul_hi_i32 v73, v72, s36
	v_mfma_f32_16x16x32_bf16 v[24:27], v[76:79], v[110:113], v[20:23]
	s_waitcnt lgkmcnt(3)
	v_mfma_f32_16x16x32_bf16 v[20:23], v[114:117], v[110:113], v[16:19]
	s_waitcnt lgkmcnt(2)
	v_mfma_f32_16x16x32_bf16 v[16:19], v[118:121], v[110:113], v[12:15]
	s_waitcnt lgkmcnt(1)
	v_mfma_f32_16x16x32_bf16 v[12:15], v[122:125], v[110:113], v[8:11]
	s_waitcnt lgkmcnt(0)
	v_mfma_f32_16x16x32_bf16 v[8:11], v[126:129], v[110:113], v[4:7]
	s_nop 2
	v_lshrrev_b32_e32 v4, 31, v73
	v_ashrrev_i32_e32 v5, 11, v73
	v_mfma_f32_16x16x32_bf16 v[56:59], v[76:79], v[106:109], v[56:59]
	v_add_u32_e32 v73, v5, v4
	v_mad_i32_i24 v78, v73, s37, v72
	v_lshlrev_b32_e32 v75, 13, v73
	v_mfma_f32_16x16x32_bf16 v[52:55], v[114:117], v[106:109], v[52:55]
	v_cmp_lt_i32_e32 vcc, s38, v78
	v_add3_u32 v74, v75, v78, s39
	v_mfma_f32_16x16x32_bf16 v[48:51], v[118:121], v[106:109], v[48:51]
	v_mfma_f32_16x16x32_bf16 v[44:47], v[122:125], v[106:109], v[44:47]
	v_mfma_f32_16x16x32_bf16 v[40:43], v[126:129], v[106:109], v[40:43]
	v_mfma_f32_16x16x32_bf16 v[4:7], v[130:133], v[110:113], v[0:3]
	v_mfma_f32_16x16x32_bf16 v[0:3], v[134:137], v[110:113], v[102:105]
	s_and_saveexec_b64 s[34:35], vcc
	s_xor_b64 s[34:35], exec, s[34:35]
	v_add3_u32 v72, v75, v78, s39
	s_or_saveexec_b64 s[34:35], s[34:35]
	v_mov_b64_e32 v[76:77], s[92:93]
	v_lshl_add_u32 v75, v73, 8, v78
	s_xor_b64 exec, exec, s[34:35]
	v_lshl_add_u32 v72, v73, 8, v78
	v_mov_b64_e32 v[76:77], s[6:7]
	s_or_b64 exec, exec, s[34:35]
	s_and_saveexec_b64 s[34:35], vcc
	s_xor_b64 s[34:35], exec, s[34:35]
	s_cbranch_execz .LBB0_1078
	v_mul_hi_i32_i24_e32 v79, 0x6000, v73
	v_mul_i32_i24_e32 v78, 0x6000, v73
	s_or_saveexec_b64 s[34:35], s[34:35]
	v_mov_b64_e32 v[80:81], s[92:93]
	s_xor_b64 exec, exec, s[34:35]
	s_cbranch_execnz .LBB0_1079
	s_branch .LBB0_1080

.LBB0_1091:
	s_add_i32 s48, s47, 0x8000
	s_and_b32 s8, s47, 0x8000
	s_and_b32 s47, s48, 0x8000
	s_add_i32 s49, s8, 0
	s_add_i32 s8, s47, 0
	s_add_u32 s71, s8, s75
	s_mov_b32 m0, s71
	s_waitcnt vmcnt(0) lgkmcnt(0)
	s_barrier
	global_load_lds_dwordx4 v236, s[84:85]
	s_add_u32 m0, s71, 0x4000
	s_nop 0
	global_load_lds_dwordx4 v237, s[72:73]
	s_add_u32 m0, s71, 0x1000
	s_nop 0
	global_load_lds_dwordx4 v238, s[84:85]
	s_add_u32 m0, s71, 0x5000
	s_nop 0
	global_load_lds_dwordx4 v239, s[72:73]
	s_add_u32 m0, s71, 0x2000
	s_nop 0
	global_load_lds_dwordx4 v240, s[84:85]
	s_add_u32 m0, s71, 0x6000
	s_nop 0
	global_load_lds_dwordx4 v241, s[72:73]
	s_add_u32 m0, s71, 0x3000
	s_nop 0
	global_load_lds_dwordx4 v242, s[84:85]
	s_add_u32 m0, s71, 0x7000
	s_nop 0
	global_load_lds_dwordx4 v243, s[72:73]
	s_add_u32 s84, s84, 0x80
	s_addc_u32 s85, s85, 0
	s_add_u32 s72, s72, 0x80
	s_addc_u32 s73, s73, 0
	v_add3_u32 v169, s49, v84, v87
	v_add3_u32 v210, s49, v87, v89
	v_add3_u32 v211, s49, v84, v90
	v_add3_u32 v212, s49, v89, v90
	ds_read_b128 v[104:107], v210
	ds_read_b128 v[68:71], v169 offset:16384
	ds_read_b128 v[100:103], v169 offset:18432
	ds_read_b128 v[108:111], v210 offset:2048
	ds_read_b128 v[112:115], v169 offset:20480
	ds_read_b128 v[116:119], v169 offset:22528
	ds_read_b128 v[120:123], v169 offset:24576
	ds_read_b128 v[124:127], v169 offset:26624
	ds_read_b128 v[128:131], v169 offset:28672
	ds_read_b128 v[132:135], v169 offset:30720
	ds_read_b128 v[178:181], v212
	ds_read_b128 v[170:173], v211 offset:16384
	ds_read_b128 v[174:177], v211 offset:18432
	ds_read_b128 v[182:185], v212 offset:2048
	ds_read_b128 v[186:189], v211 offset:20480
	ds_read_b128 v[190:193], v211 offset:22528
	ds_read_b128 v[194:197], v211 offset:24576
	ds_read_b128 v[198:201], v211 offset:26624
	ds_read_b128 v[202:205], v211 offset:28672
	ds_read_b128 v[206:209], v211 offset:30720
	s_add_u32 s36, s36, 0x80
	s_addc_u32 s37, s37, 0
	s_cmpk_eq_i32 s36, 0x780
	s_mov_b32 s47, s48
	s_waitcnt lgkmcnt(15)
	v_mfma_f32_16x16x32_bf16 v[60:63], v[68:71], v[104:107], v[60:63]
	v_mfma_f32_16x16x32_bf16 v[56:59], v[100:103], v[104:107], v[56:59]
	v_mfma_f32_16x16x32_bf16 v[52:55], v[112:115], v[104:107], v[52:55]
	s_waitcnt lgkmcnt(14)
	v_mfma_f32_16x16x32_bf16 v[48:51], v[116:119], v[104:107], v[48:51]
	s_waitcnt lgkmcnt(13)
	v_mfma_f32_16x16x32_bf16 v[44:47], v[120:123], v[104:107], v[44:47]
	s_waitcnt lgkmcnt(12)
	v_mfma_f32_16x16x32_bf16 v[40:43], v[124:127], v[104:107], v[40:43]
	s_waitcnt lgkmcnt(11)
	v_mfma_f32_16x16x32_bf16 v[36:39], v[128:131], v[104:107], v[36:39]
	s_waitcnt lgkmcnt(10)
	v_mfma_f32_16x16x32_bf16 v[32:35], v[132:135], v[104:107], v[32:35]
	v_mfma_f32_16x16x32_bf16 v[28:31], v[68:71], v[108:111], v[28:31]
	v_mfma_f32_16x16x32_bf16 v[24:27], v[100:103], v[108:111], v[24:27]
	v_mfma_f32_16x16x32_bf16 v[16:19], v[112:115], v[108:111], v[16:19]
	v_mfma_f32_16x16x32_bf16 v[12:15], v[116:119], v[108:111], v[12:15]
	v_mfma_f32_16x16x32_bf16 v[8:11], v[120:123], v[108:111], v[8:11]
	v_mfma_f32_16x16x32_bf16 v[4:7], v[124:127], v[108:111], v[4:7]
	v_mfma_f32_16x16x32_bf16 v[0:3], v[128:131], v[108:111], v[0:3]
	v_mfma_f32_16x16x32_bf16 v[20:23], v[132:135], v[108:111], v[20:23]
	s_waitcnt lgkmcnt(8)
	v_mfma_f32_16x16x32_bf16 v[60:63], v[170:173], v[178:181], v[60:63]
	s_waitcnt lgkmcnt(7)
	v_mfma_f32_16x16x32_bf16 v[56:59], v[174:177], v[178:181], v[56:59]
	s_waitcnt lgkmcnt(5)
	v_mfma_f32_16x16x32_bf16 v[52:55], v[186:189], v[178:181], v[52:55]
	s_waitcnt lgkmcnt(4)
	v_mfma_f32_16x16x32_bf16 v[48:51], v[190:193], v[178:181], v[48:51]
	s_waitcnt lgkmcnt(3)
	v_mfma_f32_16x16x32_bf16 v[44:47], v[194:197], v[178:181], v[44:47]
	s_waitcnt lgkmcnt(2)
	v_mfma_f32_16x16x32_bf16 v[40:43], v[198:201], v[178:181], v[40:43]
	s_waitcnt lgkmcnt(1)
	v_mfma_f32_16x16x32_bf16 v[36:39], v[202:205], v[178:181], v[36:39]
	s_waitcnt lgkmcnt(0)
	v_mfma_f32_16x16x32_bf16 v[32:35], v[206:209], v[178:181], v[32:35]
	v_mfma_f32_16x16x32_bf16 v[28:31], v[170:173], v[182:185], v[28:31]
	v_mfma_f32_16x16x32_bf16 v[24:27], v[174:177], v[182:185], v[24:27]
	v_mfma_f32_16x16x32_bf16 v[16:19], v[186:189], v[182:185], v[16:19]
	v_mfma_f32_16x16x32_bf16 v[12:15], v[190:193], v[182:185], v[12:15]
	v_mfma_f32_16x16x32_bf16 v[8:11], v[194:197], v[182:185], v[8:11]
	v_mfma_f32_16x16x32_bf16 v[4:7], v[198:201], v[182:185], v[4:7]
	v_mfma_f32_16x16x32_bf16 v[0:3], v[202:205], v[182:185], v[0:3]
	v_mfma_f32_16x16x32_bf16 v[20:23], v[206:209], v[182:185], v[20:23]
	s_cbranch_scc0 .LBB0_1091
	v_lshl_add_u32 v99, s46, 7, v85
	v_mul_hi_i32 v64, v99, s39
	v_lshrrev_b32_e32 v65, 31, v64
	v_ashrrev_i32_e32 v64, 11, v64
	v_add_u32_e32 v64, v64, v65
	v_mad_i32_i24 v65, v64, s40, v99
	v_cmp_lt_i32_e32 vcc, s41, v65
	v_lshl_or_b32 v72, s45, 9, v86
	s_waitcnt vmcnt(0)
	v_cndmask_b32_e32 v64, 2, v64, vcc
	v_mul_hi_i32_i24_e32 v65, 0x6000, v64
	v_mul_i32_i24_e32 v64, 0x6000, v64
	v_lshl_add_u64 v[64:65], s[94:95], 0, v[64:65]
	v_lshl_add_u64 v[150:151], v[64:65], 0, s[34:35]
	v_lshl_add_u64 v[64:65], v[150:151], 0, v[72:73]
	s_barrier
	global_load_dwordx4 v[100:103], v[64:65], off
	v_add3_u32 v64, s8, v87, v89
	v_add_u32_e32 v68, s8, v84
	ds_read_b128 v[104:107], v64
	ds_read_b128 v[108:111], v64 offset:2048
	v_add3_u32 v65, s8, v90, v89
	v_add_u32_e32 v145, v68, v87
	ds_read_b128 v[112:115], v65
	ds_read_b128 v[64:67], v65 offset:2048
	v_add_u32_e32 v168, v68, v90
	ds_read_b128 v[116:119], v145 offset:16384
	ds_read_b128 v[120:123], v145 offset:18432
	ds_read_b128 v[124:127], v168 offset:16384
	ds_read_b128 v[68:71], v168 offset:18432
	v_mul_hi_i32 v128, v99, s38
	s_waitcnt lgkmcnt(3)
	v_mfma_f32_16x16x32_bf16 v[60:63], v[116:119], v[104:107], v[60:63]
	v_lshrrev_b32_e32 v129, 31, v128
	v_lshrrev_b32_e32 v128, 11, v128
	v_add_u32_e32 v128, v128, v129
	v_lshl_add_u32 v128, v128, 13, v99
	s_lshl_b32 s8, s44, 9
	v_ashrrev_i32_e32 v129, 31, v128
	s_waitcnt lgkmcnt(1)
	v_mfma_f32_16x16x32_bf16 v[60:63], v[124:127], v[112:115], v[60:63]
	v_lshl_add_u64 v[128:129], v[128:129], 0, s[8:9]
	v_lshlrev_b64 v[128:129], 12, v[128:129]
	v_lshl_add_u64 v[128:129], s[6:7], 0, v[128:129]
	v_mov_b32_e32 v153, v73
	v_or_b32_e32 v152, 16, v72
	v_lshl_add_u64 v[154:155], v[128:129], 0, v[72:73]
	v_lshl_add_u64 v[128:129], v[150:151], 0, v[152:153]
	v_mfma_f32_16x16x32_bf16 v[56:59], v[120:123], v[104:107], v[56:59]
	v_mov_b32_e32 v157, v73
	v_or_b32_e32 v156, 0x80, v72
	v_mov_b32_e32 v159, v73
	s_waitcnt lgkmcnt(0)
	v_mfma_f32_16x16x32_bf16 v[56:59], v[68:71], v[112:115], v[56:59]
	v_or_b32_e32 v158, 0x90, v72
	v_lshl_add_u64 v[136:137], v[150:151], 0, v[158:159]
	v_mov_b32_e32 v161, v73
	v_or_b32_e32 v160, 0x100, v72
	v_mov_b32_e32 v163, v73
	v_or_b32_e32 v162, 0x110, v72
	v_lshl_add_u64 v[146:147], v[150:151], 0, v[162:163]
	v_mov_b32_e32 v165, v73
	v_or_b32_e32 v164, 0x180, v72
	v_lshl_add_u64 v[166:167], v[150:151], 0, v[164:165]
	v_mfma_f32_16x16x32_bf16 v[28:31], v[116:119], v[108:111], v[28:31]
	v_or_b32_e32 v99, 16, v99
	s_add_i32 s43, s43, s33
	s_add_i32 s42, s42, s33
	v_mfma_f32_16x16x32_bf16 v[28:31], v[124:127], v[64:67], v[28:31]
	s_cmpk_gt_i32 s43, 0x7f
	s_waitcnt vmcnt(0)
	v_pk_mul_f32 v[62:63], v[62:63], v[102:103]
	v_pk_mul_f32 v[60:61], v[60:61], v[100:101]
	global_store_dwordx4 v[154:155], v[60:63], off
	global_load_dwordx4 v[60:63], v[128:129], off
	v_lshl_add_u64 v[100:101], v[150:151], 0, v[156:157]
	v_mfma_f32_16x16x32_bf16 v[24:27], v[120:123], v[108:111], v[24:27]
	s_waitcnt vmcnt(0)
	v_pk_mul_f32 v[58:59], v[58:59], v[62:63]
	v_pk_mul_f32 v[56:57], v[56:57], v[60:61]
	global_store_dwordx4 v[154:155], v[56:59], off offset:16
	global_load_dwordx4 v[56:59], v[100:101], off
	ds_read_b128 v[60:63], v145 offset:20480
	ds_read_b128 v[100:103], v168 offset:20480
	s_waitcnt lgkmcnt(1)
	v_mfma_f32_16x16x32_bf16 v[52:55], v[60:63], v[104:107], v[52:55]
	ds_read_b128 v[128:131], v145 offset:22528
	ds_read_b128 v[132:135], v168 offset:22528
	s_waitcnt lgkmcnt(2)
	v_mfma_f32_16x16x32_bf16 v[52:55], v[100:103], v[112:115], v[52:55]
	s_waitcnt lgkmcnt(1)
	v_mfma_f32_16x16x32_bf16 v[48:51], v[128:131], v[104:107], v[48:51]
	s_waitcnt vmcnt(0)
	s_nop 4
	v_pk_mul_f32 v[54:55], v[54:55], v[58:59]
	v_pk_mul_f32 v[52:53], v[52:53], v[56:57]
	global_store_dwordx4 v[154:155], v[52:55], off offset:128
	global_load_dwordx4 v[52:55], v[136:137], off
	s_waitcnt lgkmcnt(0)
	v_mfma_f32_16x16x32_bf16 v[48:51], v[132:135], v[112:115], v[48:51]
	v_lshl_add_u64 v[56:57], v[150:151], 0, v[160:161]
	v_mfma_f32_16x16x32_bf16 v[24:27], v[68:71], v[64:67], v[24:27]
	v_mfma_f32_16x16x32_bf16 v[16:19], v[60:63], v[108:111], v[16:19]
	s_waitcnt vmcnt(0)
	s_nop 3
	v_pk_mul_f32 v[50:51], v[50:51], v[54:55]
	v_pk_mul_f32 v[48:49], v[48:49], v[52:53]
	global_store_dwordx4 v[154:155], v[48:51], off offset:144
	global_load_dwordx4 v[48:51], v[56:57], off
	ds_read_b128 v[52:55], v145 offset:24576
	ds_read_b128 v[56:59], v168 offset:24576
	s_waitcnt lgkmcnt(1)
	v_mfma_f32_16x16x32_bf16 v[44:47], v[52:55], v[104:107], v[44:47]
	ds_read_b128 v[136:139], v145 offset:26624
	ds_read_b128 v[140:143], v168 offset:26624
	s_waitcnt lgkmcnt(2)
	v_mfma_f32_16x16x32_bf16 v[44:47], v[56:59], v[112:115], v[44:47]
	s_waitcnt lgkmcnt(1)
	v_mfma_f32_16x16x32_bf16 v[40:43], v[136:139], v[104:107], v[40:43]
	s_waitcnt vmcnt(0)
	s_nop 4
	v_pk_mul_f32 v[46:47], v[46:47], v[50:51]
	v_pk_mul_f32 v[44:45], v[44:45], v[48:49]
	global_store_dwordx4 v[154:155], v[44:47], off offset:256
	global_load_dwordx4 v[44:47], v[146:147], off
	s_waitcnt lgkmcnt(0)
	v_mfma_f32_16x16x32_bf16 v[40:43], v[140:143], v[112:115], v[40:43]
	ds_read_b128 v[48:51], v145 offset:28672
	ds_read_b128 v[146:149], v145 offset:30720
	s_waitcnt lgkmcnt(1)
	v_mfma_f32_16x16x32_bf16 v[36:39], v[48:51], v[104:107], v[36:39]
	s_waitcnt vmcnt(0)
	s_nop 2
	v_pk_mul_f32 v[42:43], v[42:43], v[46:47]
	v_pk_mul_f32 v[40:41], v[40:41], v[44:45]
	global_store_dwordx4 v[154:155], v[40:43], off offset:272
	global_load_dwordx4 v[40:43], v[166:167], off
	ds_read_b128 v[44:47], v168 offset:28672
	s_waitcnt lgkmcnt(1)
	v_mfma_f32_16x16x32_bf16 v[32:35], v[146:149], v[104:107], v[32:35]
	ds_read_b128 v[104:107], v168 offset:30720
	v_mov_b32_e32 v167, v73
	v_or_b32_e32 v166, 0x190, v72
	s_waitcnt lgkmcnt(1)
	v_mfma_f32_16x16x32_bf16 v[36:39], v[44:47], v[112:115], v[36:39]
	v_lshl_add_u64 v[116:117], v[150:151], 0, v[166:167]
	s_waitcnt vmcnt(0)
	s_nop 5
	v_pk_mul_f32 v[38:39], v[38:39], v[42:43]
	v_pk_mul_f32 v[36:37], v[36:37], v[40:41]
	global_store_dwordx4 v[154:155], v[36:39], off offset:384
	global_load_dwordx4 v[36:39], v[116:117], off
	v_mul_hi_i32 v40, v99, s39
	v_lshrrev_b32_e32 v41, 31, v40
	v_ashrrev_i32_e32 v40, 11, v40
	v_add_u32_e32 v40, v40, v41
	v_mad_i32_i24 v41, v40, s40, v99
	v_cmp_lt_i32_e32 vcc, s41, v41
	s_waitcnt lgkmcnt(0)
	v_mfma_f32_16x16x32_bf16 v[32:35], v[104:107], v[112:115], v[32:35]
	v_cndmask_b32_e32 v40, 2, v40, vcc
	v_mul_hi_i32_i24_e32 v41, 0x6000, v40
	v_mul_i32_i24_e32 v40, 0x6000, v40
	v_lshl_add_u64 v[40:41], s[94:95], 0, v[40:41]
	v_lshl_add_u64 v[40:41], v[40:41], 0, s[34:35]
	v_lshl_add_u64 v[42:43], v[40:41], 0, v[72:73]
	v_mfma_f32_16x16x32_bf16 v[16:19], v[100:103], v[64:67], v[16:19]
	s_waitcnt vmcnt(0)
	v_pk_mul_f32 v[34:35], v[34:35], v[38:39]
	v_pk_mul_f32 v[32:33], v[32:33], v[36:37]
	global_store_dwordx4 v[154:155], v[32:35], off offset:400
	global_load_dwordx4 v[32:35], v[42:43], off
	v_mul_hi_i32 v36, v99, s38
	v_lshrrev_b32_e32 v37, 31, v36
	v_lshrrev_b32_e32 v36, 11, v36
	v_add_u32_e32 v36, v36, v37
	v_lshl_add_u32 v36, v36, 13, v99
	v_ashrrev_i32_e32 v37, 31, v36
	v_lshl_add_u64 v[36:37], v[36:37], 0, s[8:9]
	v_lshlrev_b64 v[36:37], 12, v[36:37]
	v_lshl_add_u64 v[36:37], s[6:7], 0, v[36:37]
	v_lshl_add_u64 v[36:37], v[36:37], 0, v[72:73]
	v_lshl_add_u64 v[38:39], v[40:41], 0, v[152:153]
	v_mfma_f32_16x16x32_bf16 v[12:15], v[128:131], v[108:111], v[12:15]
	s_waitcnt vmcnt(0)
	v_pk_mul_f32 v[30:31], v[30:31], v[34:35]
	v_pk_mul_f32 v[28:29], v[28:29], v[32:33]
	global_store_dwordx4 v[36:37], v[28:31], off
	global_load_dwordx4 v[28:31], v[38:39], off
	v_lshl_add_u64 v[32:33], v[40:41], 0, v[156:157]
	v_mfma_f32_16x16x32_bf16 v[12:15], v[132:135], v[64:67], v[12:15]
	s_waitcnt vmcnt(0)
	v_pk_mul_f32 v[26:27], v[26:27], v[30:31]
	v_pk_mul_f32 v[24:25], v[24:25], v[28:29]
	global_store_dwordx4 v[36:37], v[24:27], off offset:16
	global_load_dwordx4 v[24:27], v[32:33], off
	v_lshl_add_u64 v[28:29], v[40:41], 0, v[158:159]
	v_mfma_f32_16x16x32_bf16 v[8:11], v[52:55], v[108:111], v[8:11]
	s_waitcnt vmcnt(0)
	v_pk_mul_f32 v[18:19], v[18:19], v[26:27]
	v_pk_mul_f32 v[16:17], v[16:17], v[24:25]
	global_store_dwordx4 v[36:37], v[16:19], off offset:128
	global_load_dwordx4 v[16:19], v[28:29], off
	v_lshl_add_u64 v[24:25], v[40:41], 0, v[160:161]
	v_mfma_f32_16x16x32_bf16 v[8:11], v[56:59], v[64:67], v[8:11]
	s_waitcnt vmcnt(0)
	v_pk_mul_f32 v[14:15], v[14:15], v[18:19]
	v_pk_mul_f32 v[12:13], v[12:13], v[16:17]
	global_store_dwordx4 v[36:37], v[12:15], off offset:144
	global_load_dwordx4 v[12:15], v[24:25], off
	v_lshl_add_u64 v[16:17], v[40:41], 0, v[162:163]
	v_mfma_f32_16x16x32_bf16 v[4:7], v[136:139], v[108:111], v[4:7]
	s_waitcnt vmcnt(0)
	v_pk_mul_f32 v[10:11], v[10:11], v[14:15]
	v_pk_mul_f32 v[8:9], v[8:9], v[12:13]
	global_store_dwordx4 v[36:37], v[8:11], off offset:256
	global_load_dwordx4 v[8:11], v[16:17], off
	v_mfma_f32_16x16x32_bf16 v[4:7], v[140:143], v[64:67], v[4:7]
	v_lshl_add_u64 v[12:13], v[40:41], 0, v[164:165]
	v_mfma_f32_16x16x32_bf16 v[0:3], v[48:51], v[108:111], v[0:3]
	v_mfma_f32_16x16x32_bf16 v[0:3], v[44:47], v[64:67], v[0:3]
	s_waitcnt vmcnt(0)
	s_nop 3
	v_pk_mul_f32 v[6:7], v[6:7], v[10:11]
	v_pk_mul_f32 v[4:5], v[4:5], v[8:9]
	global_store_dwordx4 v[36:37], v[4:7], off offset:272
	global_load_dwordx4 v[4:7], v[12:13], off
	v_lshl_add_u64 v[8:9], v[40:41], 0, v[166:167]
	v_mfma_f32_16x16x32_bf16 v[20:23], v[146:149], v[108:111], v[20:23]
	s_waitcnt vmcnt(0)
	v_pk_mul_f32 v[2:3], v[2:3], v[6:7]
	v_pk_mul_f32 v[0:1], v[0:1], v[4:5]
	global_store_dwordx4 v[36:37], v[0:3], off offset:384
	global_load_dwordx4 v[0:3], v[8:9], off
	v_mfma_f32_16x16x32_bf16 v[4:7], v[104:107], v[64:67], v[20:23]
	s_waitcnt vmcnt(0)
	s_nop 6
	v_pk_mul_f32 v[2:3], v[6:7], v[2:3]
	v_pk_mul_f32 v[0:1], v[4:5], v[0:1]
	global_store_dwordx4 v[36:37], v[0:3], off offset:400
	s_cbranch_scc0 .LBB0_1090

.LBB0_1217:
	s_add_i32 s41, s3, 0x8000
	s_and_b32 s40, s41, 0x8000
	s_add_i32 s40, s40, 0
	s_add_u32 s86, s40, s87
	s_mov_b32 m0, s86
	s_waitcnt vmcnt(0) lgkmcnt(0)
	s_barrier
	global_load_lds_dwordx4 v244, s[96:97]
	s_add_u32 m0, s86, 0x4000
	s_nop 0
	global_load_lds_dwordx4 v245, s[88:89]
	s_add_u32 m0, s86, 0x1000
	s_nop 0
	global_load_lds_dwordx4 v246, s[96:97]
	s_add_u32 m0, s86, 0x5000
	s_nop 0
	global_load_lds_dwordx4 v247, s[88:89]
	s_add_u32 m0, s86, 0x2000
	s_nop 0
	global_load_lds_dwordx4 v248, s[96:97]
	s_add_u32 m0, s86, 0x6000
	s_nop 0
	global_load_lds_dwordx4 v249, s[88:89]
	s_add_u32 m0, s86, 0x3000
	s_nop 0
	global_load_lds_dwordx4 v250, s[96:97]
	s_add_u32 m0, s86, 0x7000
	s_nop 0
	global_load_lds_dwordx4 v251, s[88:89]
	s_add_u32 s96, s96, 0x80
	s_addc_u32 s97, s97, 0
	s_add_u32 s88, s88, 0x80
	s_addc_u32 s89, s89, 0
	s_and_b32 s3, s3, 0x8000
	s_add_i32 s3, s3, 0
	v_add3_u32 v145, s3, v87, v88
	v_add3_u32 v186, s3, v88, v89
	v_add3_u32 v187, s3, v87, v90
	v_add3_u32 v188, s3, v89, v90
	ds_read_b128 v[112:115], v186
	ds_read_b128 v[104:107], v145 offset:16384
	ds_read_b128 v[108:111], v145 offset:18432
	ds_read_b128 v[116:119], v186 offset:2048
	ds_read_b128 v[120:123], v145 offset:20480
	ds_read_b128 v[124:127], v145 offset:22528
	ds_read_b128 v[128:131], v145 offset:24576
	ds_read_b128 v[132:135], v145 offset:26624
	ds_read_b128 v[136:139], v145 offset:28672
	ds_read_b128 v[140:143], v145 offset:30720
	ds_read_b128 v[154:157], v188
	ds_read_b128 v[146:149], v187 offset:16384
	ds_read_b128 v[150:153], v187 offset:18432
	ds_read_b128 v[158:161], v188 offset:2048
	ds_read_b128 v[162:165], v187 offset:20480
	ds_read_b128 v[166:169], v187 offset:22528
	ds_read_b128 v[170:173], v187 offset:24576
	ds_read_b128 v[174:177], v187 offset:26624
	ds_read_b128 v[178:181], v187 offset:28672
	ds_read_b128 v[182:185], v187 offset:30720
	s_add_u32 s0, s0, 0x80
	s_addc_u32 s1, s1, 0
	s_cmpk_eq_i32 s0, 0x780
	s_mov_b32 s3, s41
	s_waitcnt lgkmcnt(15)
	v_mfma_f32_16x16x32_bf16 v[60:63], v[104:107], v[112:115], v[60:63]
	v_mfma_f32_16x16x32_bf16 v[56:59], v[108:111], v[112:115], v[56:59]
	v_mfma_f32_16x16x32_bf16 v[52:55], v[120:123], v[112:115], v[52:55]
	s_waitcnt lgkmcnt(14)
	v_mfma_f32_16x16x32_bf16 v[48:51], v[124:127], v[112:115], v[48:51]
	s_waitcnt lgkmcnt(13)
	v_mfma_f32_16x16x32_bf16 v[44:47], v[128:131], v[112:115], v[44:47]
	s_waitcnt lgkmcnt(12)
	v_mfma_f32_16x16x32_bf16 v[36:39], v[132:135], v[112:115], v[36:39]
	s_waitcnt lgkmcnt(11)
	v_mfma_f32_16x16x32_bf16 v[32:35], v[136:139], v[112:115], v[32:35]
	s_waitcnt lgkmcnt(10)
	v_mfma_f32_16x16x32_bf16 v[28:31], v[140:143], v[112:115], v[28:31]
	v_mfma_f32_16x16x32_bf16 v[24:27], v[104:107], v[116:119], v[24:27]
	v_mfma_f32_16x16x32_bf16 v[20:23], v[108:111], v[116:119], v[20:23]
	v_mfma_f32_16x16x32_bf16 v[16:19], v[120:123], v[116:119], v[16:19]
	v_mfma_f32_16x16x32_bf16 v[12:15], v[124:127], v[116:119], v[12:15]
	v_mfma_f32_16x16x32_bf16 v[8:11], v[128:131], v[116:119], v[8:11]
	v_mfma_f32_16x16x32_bf16 v[4:7], v[132:135], v[116:119], v[4:7]
	v_mfma_f32_16x16x32_bf16 v[0:3], v[136:139], v[116:119], v[0:3]
	v_mfma_f32_16x16x32_bf16 v[40:43], v[140:143], v[116:119], v[40:43]
	s_waitcnt lgkmcnt(8)
	v_mfma_f32_16x16x32_bf16 v[60:63], v[146:149], v[154:157], v[60:63]
	s_waitcnt lgkmcnt(7)
	v_mfma_f32_16x16x32_bf16 v[56:59], v[150:153], v[154:157], v[56:59]
	s_waitcnt lgkmcnt(5)
	v_mfma_f32_16x16x32_bf16 v[52:55], v[162:165], v[154:157], v[52:55]
	s_waitcnt lgkmcnt(4)
	v_mfma_f32_16x16x32_bf16 v[48:51], v[166:169], v[154:157], v[48:51]
	s_waitcnt lgkmcnt(3)
	v_mfma_f32_16x16x32_bf16 v[44:47], v[170:173], v[154:157], v[44:47]
	s_waitcnt lgkmcnt(2)
	v_mfma_f32_16x16x32_bf16 v[36:39], v[174:177], v[154:157], v[36:39]
	s_waitcnt lgkmcnt(1)
	v_mfma_f32_16x16x32_bf16 v[32:35], v[178:181], v[154:157], v[32:35]
	s_waitcnt lgkmcnt(0)
	v_mfma_f32_16x16x32_bf16 v[28:31], v[182:185], v[154:157], v[28:31]
	v_mfma_f32_16x16x32_bf16 v[24:27], v[146:149], v[158:161], v[24:27]
	v_mfma_f32_16x16x32_bf16 v[20:23], v[150:153], v[158:161], v[20:23]
	v_mfma_f32_16x16x32_bf16 v[16:19], v[162:165], v[158:161], v[16:19]
	v_mfma_f32_16x16x32_bf16 v[12:15], v[166:169], v[158:161], v[12:15]
	v_mfma_f32_16x16x32_bf16 v[8:11], v[170:173], v[158:161], v[8:11]
	v_mfma_f32_16x16x32_bf16 v[4:7], v[174:177], v[158:161], v[4:7]
	v_mfma_f32_16x16x32_bf16 v[0:3], v[178:181], v[158:161], v[0:3]
	v_mfma_f32_16x16x32_bf16 v[40:43], v[182:185], v[158:161], v[40:43]
	s_cbranch_scc0 .LBB0_1217
	v_add_u32_e32 v64, s40, v87
	v_add_u32_e32 v103, v64, v88
	v_add3_u32 v112, s40, v88, v89
	s_waitcnt vmcnt(0)
	s_barrier
	ds_read_b128 v[82:85], v103 offset:16384
	ds_read_b128 v[104:107], v103 offset:18432
	ds_read_b128 v[108:111], v112
	ds_read_b128 v[112:115], v112 offset:2048
	ds_read_b128 v[116:119], v103 offset:20480
	ds_read_b128 v[120:123], v103 offset:22528
	ds_read_b128 v[124:127], v103 offset:24576
	ds_read_b128 v[128:131], v103 offset:26624
	ds_read_b128 v[132:135], v103 offset:28672
	ds_read_b128 v[136:139], v103 offset:30720
	v_add_u32_e32 v64, v64, v90
	s_waitcnt lgkmcnt(7)
	v_mfma_f32_16x16x32_bf16 v[60:63], v[82:85], v[108:111], v[60:63]
	s_mul_hi_i32 s0, s2, 0x3e0f83e1
	s_lshr_b32 s1, s0, 31
	s_ashr_i32 s56, s0, 4
	v_mfma_f32_16x16x32_bf16 v[56:59], v[104:107], v[108:111], v[56:59]
	s_add_i32 s56, s56, s1
	s_cmp_gt_i32 s39, 11
	s_cselect_b64 s[0:1], -1, 0
	s_waitcnt lgkmcnt(4)
	v_mfma_f32_16x16x32_bf16 v[48:51], v[120:123], v[108:111], v[48:51]
	s_lshl_b32 s53, s2, 7
	s_cmp_lt_i32 s39, 12
	s_mul_i32 s54, s56, 0xffffdf00
	s_waitcnt lgkmcnt(3)
	v_mfma_f32_16x16x32_bf16 v[44:47], v[124:127], v[108:111], v[44:47]
	s_waitcnt lgkmcnt(2)
	v_mfma_f32_16x16x32_bf16 v[36:39], v[128:131], v[108:111], v[36:39]
	s_waitcnt lgkmcnt(1)
	v_mfma_f32_16x16x32_bf16 v[32:35], v[132:135], v[108:111], v[32:35]
	s_waitcnt lgkmcnt(0)
	v_mfma_f32_16x16x32_bf16 v[28:31], v[136:139], v[108:111], v[28:31]
	v_mfma_f32_16x16x32_bf16 v[24:27], v[82:85], v[112:115], v[24:27]
	ds_read_b128 v[82:85], v64 offset:16384
	v_mfma_f32_16x16x32_bf16 v[52:55], v[116:119], v[108:111], v[52:55]
	v_mfma_f32_16x16x32_bf16 v[20:23], v[104:107], v[112:115], v[20:23]
	v_mfma_f32_16x16x32_bf16 v[16:19], v[116:119], v[112:115], v[16:19]
	v_mfma_f32_16x16x32_bf16 v[12:15], v[120:123], v[112:115], v[12:15]
	v_mfma_f32_16x16x32_bf16 v[8:11], v[124:127], v[112:115], v[8:11]
	v_mfma_f32_16x16x32_bf16 v[4:7], v[128:131], v[112:115], v[4:7]
	v_mfma_f32_16x16x32_bf16 v[0:3], v[132:135], v[112:115], v[0:3]
	v_mfma_f32_16x16x32_bf16 v[104:107], v[136:139], v[112:115], v[40:43]
	s_nop 2
	v_add3_u32 v40, s40, v90, v89
	ds_read_b128 v[108:111], v64 offset:18432
	ds_read_b128 v[112:115], v40
	ds_read_b128 v[116:119], v40 offset:2048
	ds_read_b128 v[120:123], v64 offset:20480
	ds_read_b128 v[124:127], v64 offset:22528
	ds_read_b128 v[128:131], v64 offset:24576
	ds_read_b128 v[132:135], v64 offset:26624
	ds_read_b128 v[136:139], v64 offset:28672
	ds_read_b128 v[140:143], v64 offset:30720
	s_waitcnt lgkmcnt(7)
	v_mfma_f32_16x16x32_bf16 v[60:63], v[82:85], v[112:115], v[60:63]
	v_mfma_f32_16x16x32_bf16 v[56:59], v[108:111], v[112:115], v[56:59]
	s_waitcnt lgkmcnt(5)
	v_mfma_f32_16x16x32_bf16 v[52:55], v[120:123], v[112:115], v[52:55]
	s_waitcnt lgkmcnt(4)
	v_mfma_f32_16x16x32_bf16 v[48:51], v[124:127], v[112:115], v[48:51]
	s_waitcnt lgkmcnt(3)
	v_mfma_f32_16x16x32_bf16 v[44:47], v[128:131], v[112:115], v[44:47]
	s_waitcnt lgkmcnt(2)
	v_mfma_f32_16x16x32_bf16 v[40:43], v[132:135], v[112:115], v[36:39]
	s_waitcnt lgkmcnt(1)
	v_mfma_f32_16x16x32_bf16 v[36:39], v[136:139], v[112:115], v[32:35]
	s_waitcnt lgkmcnt(0)
	v_mfma_f32_16x16x32_bf16 v[32:35], v[140:143], v[112:115], v[28:31]
	v_mfma_f32_16x16x32_bf16 v[28:31], v[82:85], v[116:119], v[24:27]
	v_mfma_f32_16x16x32_bf16 v[24:27], v[108:111], v[116:119], v[20:23]
	v_mfma_f32_16x16x32_bf16 v[20:23], v[120:123], v[116:119], v[16:19]
	v_mfma_f32_16x16x32_bf16 v[16:19], v[124:127], v[116:119], v[12:15]
	v_mfma_f32_16x16x32_bf16 v[12:15], v[128:131], v[116:119], v[8:11]
	v_mfma_f32_16x16x32_bf16 v[8:11], v[132:135], v[116:119], v[4:7]
	v_mfma_f32_16x16x32_bf16 v[4:7], v[136:139], v[116:119], v[0:3]
	v_mfma_f32_16x16x32_bf16 v[0:3], v[140:143], v[116:119], v[104:107]
	s_cbranch_scc0 .LBB0_1224
	s_add_i32 s40, s54, s53
	v_add_u32_e32 v64, s40, v70
	v_cmp_lt_i32_e32 vcc, s48, v64
	s_and_saveexec_b64 s[2:3], vcc
	s_cbranch_execz .LBB0_1221
	v_lshl_add_u32 v64, v64, 5, v102
	v_lshlrev_b64 v[108:109], 2, v[64:65]
	v_lshl_add_u64 v[104:105], v[76:77], 0, v[108:109]
	global_load_dwordx4 v[82:85], v[104:105], off
	s_nop 0
	global_load_dwordx4 v[104:107], v[104:105], off offset:16
	v_lshl_add_u64 v[112:113], v[74:75], 0, v[108:109]
	global_load_dwordx4 v[108:111], v[112:113], off
	s_nop 0
	global_load_dwordx4 v[112:115], v[112:113], off offset:16
	s_waitcnt vmcnt(3)
	v_pk_mul_f32 v[116:117], v[54:55], v[84:85]
	v_pk_mul_f32 v[118:119], v[52:53], v[82:83]
	v_pk_mul_f32 v[120:121], v[62:63], v[84:85]
	v_pk_mul_f32 v[122:123], v[60:61], v[82:83]
	s_waitcnt vmcnt(2)
	v_pk_mul_f32 v[124:125], v[50:51], v[106:107]
	v_pk_mul_f32 v[126:127], v[48:49], v[104:105]
	v_pk_mul_f32 v[128:129], v[58:59], v[106:107]
	v_pk_mul_f32 v[130:131], v[56:57], v[104:105]
	v_pk_mul_f32 v[132:133], v[38:39], v[84:85]
	v_pk_mul_f32 v[134:135], v[36:37], v[82:83]
	v_pk_mul_f32 v[84:85], v[46:47], v[84:85]
	v_pk_mul_f32 v[82:83], v[44:45], v[82:83]
	v_pk_mul_f32 v[136:137], v[34:35], v[106:107]
	v_pk_mul_f32 v[138:139], v[32:33], v[104:105]
	v_pk_mul_f32 v[106:107], v[42:43], v[106:107]
	v_pk_mul_f32 v[104:105], v[40:41], v[104:105]
	s_waitcnt vmcnt(1)
	v_pk_fma_f32 v[62:63], v[62:63], v[110:111], v[116:117] neg_lo:[0,0,1] neg_hi:[0,0,1]
	v_pk_fma_f32 v[60:61], v[60:61], v[108:109], v[118:119] neg_lo:[0,0,1] neg_hi:[0,0,1]
	v_pk_fma_f32 v[54:55], v[54:55], v[110:111], v[120:121]
	v_pk_fma_f32 v[52:53], v[52:53], v[108:109], v[122:123]
	s_waitcnt vmcnt(0)
	v_pk_fma_f32 v[58:59], v[58:59], v[114:115], v[124:125] neg_lo:[0,0,1] neg_hi:[0,0,1]
	v_pk_fma_f32 v[56:57], v[56:57], v[112:113], v[126:127] neg_lo:[0,0,1] neg_hi:[0,0,1]
	v_pk_fma_f32 v[50:51], v[50:51], v[114:115], v[128:129]
	v_pk_fma_f32 v[48:49], v[48:49], v[112:113], v[130:131]
	v_pk_fma_f32 v[46:47], v[46:47], v[110:111], v[132:133] neg_lo:[0,0,1] neg_hi:[0,0,1]
	v_pk_fma_f32 v[44:45], v[44:45], v[108:109], v[134:135] neg_lo:[0,0,1] neg_hi:[0,0,1]
	v_pk_fma_f32 v[38:39], v[38:39], v[110:111], v[84:85]
	v_pk_fma_f32 v[36:37], v[36:37], v[108:109], v[82:83]
	v_pk_fma_f32 v[42:43], v[42:43], v[114:115], v[136:137] neg_lo:[0,0,1] neg_hi:[0,0,1]
	v_pk_fma_f32 v[40:41], v[40:41], v[112:113], v[138:139] neg_lo:[0,0,1] neg_hi:[0,0,1]
	v_pk_fma_f32 v[34:35], v[34:35], v[114:115], v[106:107]
	v_pk_fma_f32 v[32:33], v[32:33], v[112:113], v[104:105]

.LBB0_1615:
	s_add_i32 s41, s39, 0x8000
	s_and_b32 s40, s41, 0x8000
	s_add_i32 s40, s40, 0
	s_add_u32 s86, s40, s87
	s_mov_b32 m0, s86
	s_waitcnt vmcnt(0) lgkmcnt(0)
	s_barrier
	global_load_lds_dwordx4 v244, s[96:97]
	s_add_u32 m0, s86, 0x4000
	s_nop 0
	global_load_lds_dwordx4 v245, s[88:89]
	s_add_u32 m0, s86, 0x1000
	s_nop 0
	global_load_lds_dwordx4 v246, s[96:97]
	s_add_u32 m0, s86, 0x5000
	s_nop 0
	global_load_lds_dwordx4 v247, s[88:89]
	s_add_u32 m0, s86, 0x2000
	s_nop 0
	global_load_lds_dwordx4 v248, s[96:97]
	s_add_u32 m0, s86, 0x6000
	s_nop 0
	global_load_lds_dwordx4 v249, s[88:89]
	s_add_u32 m0, s86, 0x3000
	s_nop 0
	global_load_lds_dwordx4 v250, s[96:97]
	s_add_u32 m0, s86, 0x7000
	s_nop 0
	global_load_lds_dwordx4 v251, s[88:89]
	s_add_u32 s96, s96, 0x80
	s_addc_u32 s97, s97, 0
	s_add_u32 s88, s88, 0x80
	s_addc_u32 s89, s89, 0
	s_and_b32 s39, s39, 0x8000
	s_add_i32 s39, s39, 0
	v_add3_u32 v145, s39, v84, v85
	v_add3_u32 v178, s39, v85, v86
	v_add3_u32 v179, s39, v84, v87
	v_add3_u32 v180, s39, v86, v87
	ds_read_b128 v[104:107], v178
	ds_read_b128 v[76:79], v145 offset:16384
	ds_read_b128 v[100:103], v145 offset:18432
	ds_read_b128 v[108:111], v178 offset:2048
	ds_read_b128 v[112:115], v145 offset:20480
	ds_read_b128 v[116:119], v145 offset:22528
	ds_read_b128 v[120:123], v145 offset:24576
	ds_read_b128 v[124:127], v145 offset:26624
	ds_read_b128 v[128:131], v145 offset:28672
	ds_read_b128 v[132:135], v145 offset:30720
	ds_read_b128 v[146:149], v180
	ds_read_b128 v[136:139], v179 offset:16384
	ds_read_b128 v[140:143], v179 offset:18432
	ds_read_b128 v[150:153], v180 offset:2048
	ds_read_b128 v[154:157], v179 offset:20480
	ds_read_b128 v[158:161], v179 offset:22528
	ds_read_b128 v[162:165], v179 offset:24576
	ds_read_b128 v[166:169], v179 offset:26624
	ds_read_b128 v[170:173], v179 offset:28672
	ds_read_b128 v[174:177], v179 offset:30720
	s_add_u32 s28, s28, 0x80
	s_addc_u32 s29, s29, 0
	s_cmpk_eq_i32 s28, 0x780
	s_mov_b32 s39, s41
	s_waitcnt lgkmcnt(15)
	v_mfma_f32_16x16x32_bf16 v[60:63], v[76:79], v[104:107], v[60:63]
	v_mfma_f32_16x16x32_bf16 v[56:59], v[100:103], v[104:107], v[56:59]
	v_mfma_f32_16x16x32_bf16 v[52:55], v[112:115], v[104:107], v[52:55]
	s_waitcnt lgkmcnt(14)
	v_mfma_f32_16x16x32_bf16 v[48:51], v[116:119], v[104:107], v[48:51]
	s_waitcnt lgkmcnt(13)
	v_mfma_f32_16x16x32_bf16 v[44:47], v[120:123], v[104:107], v[44:47]
	s_waitcnt lgkmcnt(12)
	v_mfma_f32_16x16x32_bf16 v[40:43], v[124:127], v[104:107], v[40:43]
	s_waitcnt lgkmcnt(11)
	v_mfma_f32_16x16x32_bf16 v[32:35], v[128:131], v[104:107], v[32:35]
	s_waitcnt lgkmcnt(10)
	v_mfma_f32_16x16x32_bf16 v[28:31], v[132:135], v[104:107], v[28:31]
	v_mfma_f32_16x16x32_bf16 v[24:27], v[76:79], v[108:111], v[24:27]
	v_mfma_f32_16x16x32_bf16 v[20:23], v[100:103], v[108:111], v[20:23]
	v_mfma_f32_16x16x32_bf16 v[16:19], v[112:115], v[108:111], v[16:19]
	v_mfma_f32_16x16x32_bf16 v[12:15], v[116:119], v[108:111], v[12:15]
	v_mfma_f32_16x16x32_bf16 v[8:11], v[120:123], v[108:111], v[8:11]
	v_mfma_f32_16x16x32_bf16 v[4:7], v[124:127], v[108:111], v[4:7]
	v_mfma_f32_16x16x32_bf16 v[0:3], v[128:131], v[108:111], v[0:3]
	v_mfma_f32_16x16x32_bf16 v[36:39], v[132:135], v[108:111], v[36:39]
	s_waitcnt lgkmcnt(8)
	v_mfma_f32_16x16x32_bf16 v[60:63], v[136:139], v[146:149], v[60:63]
	s_waitcnt lgkmcnt(7)
	v_mfma_f32_16x16x32_bf16 v[56:59], v[140:143], v[146:149], v[56:59]
	s_waitcnt lgkmcnt(5)
	v_mfma_f32_16x16x32_bf16 v[52:55], v[154:157], v[146:149], v[52:55]
	s_waitcnt lgkmcnt(4)
	v_mfma_f32_16x16x32_bf16 v[48:51], v[158:161], v[146:149], v[48:51]
	s_waitcnt lgkmcnt(3)
	v_mfma_f32_16x16x32_bf16 v[44:47], v[162:165], v[146:149], v[44:47]
	s_waitcnt lgkmcnt(2)
	v_mfma_f32_16x16x32_bf16 v[40:43], v[166:169], v[146:149], v[40:43]
	s_waitcnt lgkmcnt(1)
	v_mfma_f32_16x16x32_bf16 v[32:35], v[170:173], v[146:149], v[32:35]
	s_waitcnt lgkmcnt(0)
	v_mfma_f32_16x16x32_bf16 v[28:31], v[174:177], v[146:149], v[28:31]
	v_mfma_f32_16x16x32_bf16 v[24:27], v[136:139], v[150:153], v[24:27]
	v_mfma_f32_16x16x32_bf16 v[20:23], v[140:143], v[150:153], v[20:23]
	v_mfma_f32_16x16x32_bf16 v[16:19], v[154:157], v[150:153], v[16:19]
	v_mfma_f32_16x16x32_bf16 v[12:15], v[158:161], v[150:153], v[12:15]
	v_mfma_f32_16x16x32_bf16 v[8:11], v[162:165], v[150:153], v[8:11]
	v_mfma_f32_16x16x32_bf16 v[4:7], v[166:169], v[150:153], v[4:7]
	v_mfma_f32_16x16x32_bf16 v[0:3], v[170:173], v[150:153], v[0:3]
	v_mfma_f32_16x16x32_bf16 v[36:39], v[174:177], v[150:153], v[36:39]
	s_cbranch_scc0 .LBB0_1615
	v_add_u32_e32 v80, s40, v84
	v_add_u32_e32 v81, v80, v85
	s_waitcnt vmcnt(0)
	s_barrier
	ds_read_b128 v[72:75], v81 offset:16384
	v_add3_u32 v99, s40, v85, v86
	ds_read_b128 v[76:79], v81 offset:18432
	ds_read_b128 v[100:103], v99
	ds_read_b128 v[104:107], v99 offset:2048
	ds_read_b128 v[108:111], v81 offset:20480
	ds_read_b128 v[112:115], v81 offset:22528
	ds_read_b128 v[116:119], v81 offset:24576
	ds_read_b128 v[120:123], v81 offset:26624
	ds_read_b128 v[124:127], v81 offset:28672
	ds_read_b128 v[128:131], v81 offset:30720
	v_add_u32_e32 v80, v80, v87
	s_waitcnt lgkmcnt(7)
	v_mfma_f32_16x16x32_bf16 v[60:63], v[72:75], v[100:103], v[60:63]
	s_lshl_b32 s38, s38, 7
	v_mfma_f32_16x16x32_bf16 v[56:59], v[76:79], v[100:103], v[56:59]
	s_waitcnt lgkmcnt(4)
	v_mfma_f32_16x16x32_bf16 v[48:51], v[112:115], v[100:103], v[48:51]
	s_waitcnt lgkmcnt(3)
	v_mfma_f32_16x16x32_bf16 v[44:47], v[116:119], v[100:103], v[44:47]
	s_waitcnt lgkmcnt(2)
	v_mfma_f32_16x16x32_bf16 v[40:43], v[120:123], v[100:103], v[40:43]
	s_waitcnt lgkmcnt(1)
	v_mfma_f32_16x16x32_bf16 v[32:35], v[124:127], v[100:103], v[32:35]
	s_waitcnt lgkmcnt(0)
	v_mfma_f32_16x16x32_bf16 v[28:31], v[128:131], v[100:103], v[28:31]
	v_mfma_f32_16x16x32_bf16 v[24:27], v[72:75], v[104:107], v[24:27]
	ds_read_b128 v[72:75], v80 offset:16384
	v_mfma_f32_16x16x32_bf16 v[52:55], v[108:111], v[100:103], v[52:55]
	v_mfma_f32_16x16x32_bf16 v[20:23], v[76:79], v[104:107], v[20:23]
	v_mfma_f32_16x16x32_bf16 v[16:19], v[108:111], v[104:107], v[16:19]
	v_mfma_f32_16x16x32_bf16 v[12:15], v[112:115], v[104:107], v[12:15]
	v_mfma_f32_16x16x32_bf16 v[8:11], v[116:119], v[104:107], v[8:11]
	v_mfma_f32_16x16x32_bf16 v[4:7], v[120:123], v[104:107], v[4:7]
	v_mfma_f32_16x16x32_bf16 v[0:3], v[124:127], v[104:107], v[0:3]
	v_mfma_f32_16x16x32_bf16 v[100:103], v[128:131], v[104:107], v[36:39]
	s_nop 2
	v_add3_u32 v36, s40, v87, v86
	ds_read_b128 v[76:79], v80 offset:18432
	ds_read_b128 v[104:107], v36
	ds_read_b128 v[108:111], v36 offset:2048
	ds_read_b128 v[128:131], v80 offset:28672
	ds_read_b128 v[132:135], v80 offset:30720
	ds_read_b128 v[112:115], v80 offset:20480
	ds_read_b128 v[116:119], v80 offset:22528
	ds_read_b128 v[120:123], v80 offset:24576
	ds_read_b128 v[124:127], v80 offset:26624
	s_waitcnt lgkmcnt(7)
	v_mfma_f32_16x16x32_bf16 v[60:63], v[72:75], v[104:107], v[60:63]
	s_waitcnt lgkmcnt(5)
	v_mfma_f32_16x16x32_bf16 v[36:39], v[128:131], v[104:107], v[32:35]
	s_waitcnt lgkmcnt(4)
	v_mfma_f32_16x16x32_bf16 v[32:35], v[132:135], v[104:107], v[28:31]
	v_mfma_f32_16x16x32_bf16 v[28:31], v[72:75], v[108:111], v[24:27]
	v_add_u32_e32 v72, s38, v83
	v_mul_hi_i32 v73, v72, s31
	v_mfma_f32_16x16x32_bf16 v[24:27], v[76:79], v[108:111], v[20:23]
	s_waitcnt lgkmcnt(3)
	v_mfma_f32_16x16x32_bf16 v[20:23], v[112:115], v[108:111], v[16:19]
	s_waitcnt lgkmcnt(2)
	v_mfma_f32_16x16x32_bf16 v[16:19], v[116:119], v[108:111], v[12:15]
	s_waitcnt lgkmcnt(1)
	v_mfma_f32_16x16x32_bf16 v[12:15], v[120:123], v[108:111], v[8:11]
	s_waitcnt lgkmcnt(0)
	v_mfma_f32_16x16x32_bf16 v[8:11], v[124:127], v[108:111], v[4:7]
	s_nop 2
	v_lshrrev_b32_e32 v4, 31, v73
	v_ashrrev_i32_e32 v5, 11, v73
	v_mfma_f32_16x16x32_bf16 v[56:59], v[76:79], v[104:107], v[56:59]
	v_add_u32_e32 v73, v5, v4
	v_mad_i32_i24 v78, v73, s33, v72
	v_lshlrev_b32_e32 v75, 13, v73
	v_mfma_f32_16x16x32_bf16 v[52:55], v[112:115], v[104:107], v[52:55]
	v_cmp_lt_i32_e32 vcc, s34, v78
	v_add3_u32 v74, v75, v78, s35
	v_mfma_f32_16x16x32_bf16 v[48:51], v[116:119], v[104:107], v[48:51]
	v_mfma_f32_16x16x32_bf16 v[44:47], v[120:123], v[104:107], v[44:47]
	v_mfma_f32_16x16x32_bf16 v[40:43], v[124:127], v[104:107], v[40:43]
	v_mfma_f32_16x16x32_bf16 v[4:7], v[128:131], v[108:111], v[0:3]
	v_mfma_f32_16x16x32_bf16 v[0:3], v[132:135], v[108:111], v[100:103]
	s_and_saveexec_b64 s[28:29], vcc
	s_xor_b64 s[28:29], exec, s[28:29]
	v_add3_u32 v72, v75, v78, s35
	s_or_saveexec_b64 s[28:29], s[28:29]
	v_mov_b64_e32 v[76:77], s[92:93]
	v_lshl_add_u32 v75, v73, 8, v78
	s_xor_b64 exec, exec, s[28:29]
	v_lshl_add_u32 v72, v73, 8, v78
	v_mov_b64_e32 v[76:77], s[2:3]
	s_or_b64 exec, exec, s[28:29]
	s_and_saveexec_b64 s[28:29], vcc
	s_xor_b64 s[28:29], exec, s[28:29]
	s_cbranch_execz .LBB0_1622
	v_add_u32_e32 v73, 3, v73
	v_mul_hi_i32_i24_e32 v79, 0x6000, v73
	v_mul_i32_i24_e32 v78, 0x6000, v73
	s_or_saveexec_b64 s[28:29], s[28:29]
	v_mov_b64_e32 v[80:81], s[92:93]
	s_xor_b64 exec, exec, s[28:29]
	s_cbranch_execnz .LBB0_1623
	s_branch .LBB0_1624

.LBB0_1759:
	s_add_i32 s36, s34, 0x8000
	s_and_b32 s35, s36, 0x8000
	s_add_i32 s35, s35, 0
	s_add_u32 s86, s35, s87
	s_mov_b32 m0, s86
	s_waitcnt vmcnt(0) lgkmcnt(0)
	s_barrier
	global_load_lds_dwordx4 v244, s[96:97]
	s_add_u32 m0, s86, 0x4000
	s_nop 0
	global_load_lds_dwordx4 v245, s[88:89]
	s_add_u32 m0, s86, 0x1000
	s_nop 0
	global_load_lds_dwordx4 v246, s[96:97]
	s_add_u32 m0, s86, 0x5000
	s_nop 0
	global_load_lds_dwordx4 v247, s[88:89]
	s_add_u32 m0, s86, 0x2000
	s_nop 0
	global_load_lds_dwordx4 v248, s[96:97]
	s_add_u32 m0, s86, 0x6000
	s_nop 0
	global_load_lds_dwordx4 v249, s[88:89]
	s_add_u32 m0, s86, 0x3000
	s_nop 0
	global_load_lds_dwordx4 v250, s[96:97]
	s_add_u32 m0, s86, 0x7000
	s_nop 0
	global_load_lds_dwordx4 v251, s[88:89]
	s_add_u32 s96, s96, 0x80
	s_addc_u32 s97, s97, 0
	s_add_u32 s88, s88, 0x80
	s_addc_u32 s89, s89, 0
	s_and_b32 s34, s34, 0x8000
	s_add_i32 s34, s34, 0
	v_add3_u32 v143, s34, v80, v81
	v_add3_u32 v145, s34, v81, v82
	v_add3_u32 v206, s34, v80, v83
	v_add3_u32 v207, s34, v82, v83
	ds_read_b128 v[102:105], v145
	ds_read_b128 v[94:97], v143 offset:16384
	ds_read_b128 v[98:101], v143 offset:18432
	ds_read_b128 v[106:109], v145 offset:2048
	ds_read_b128 v[110:113], v143 offset:20480
	ds_read_b128 v[114:117], v143 offset:22528
	ds_read_b128 v[118:121], v143 offset:24576
	ds_read_b128 v[122:125], v143 offset:26624
	ds_read_b128 v[126:129], v143 offset:28672
	ds_read_b128 v[130:133], v143 offset:30720
	ds_read_b128 v[174:177], v207
	ds_read_b128 v[166:169], v206 offset:16384
	ds_read_b128 v[170:173], v206 offset:18432
	ds_read_b128 v[178:181], v207 offset:2048
	ds_read_b128 v[182:185], v206 offset:20480
	ds_read_b128 v[186:189], v206 offset:22528
	ds_read_b128 v[190:193], v206 offset:24576
	ds_read_b128 v[194:197], v206 offset:26624
	ds_read_b128 v[198:201], v206 offset:28672
	ds_read_b128 v[202:205], v206 offset:30720
	s_add_u32 s26, s26, 0x80
	s_addc_u32 s27, s27, 0
	s_cmpk_eq_i32 s26, 0x780
	s_mov_b32 s34, s36
	s_waitcnt lgkmcnt(15)
	v_mfma_f32_16x16x32_bf16 v[60:63], v[94:97], v[102:105], v[60:63]
	v_mfma_f32_16x16x32_bf16 v[56:59], v[98:101], v[102:105], v[56:59]
	v_mfma_f32_16x16x32_bf16 v[52:55], v[110:113], v[102:105], v[52:55]
	s_waitcnt lgkmcnt(14)
	v_mfma_f32_16x16x32_bf16 v[48:51], v[114:117], v[102:105], v[48:51]
	s_waitcnt lgkmcnt(13)
	v_mfma_f32_16x16x32_bf16 v[44:47], v[118:121], v[102:105], v[44:47]
	s_waitcnt lgkmcnt(12)
	v_mfma_f32_16x16x32_bf16 v[40:43], v[122:125], v[102:105], v[40:43]
	s_waitcnt lgkmcnt(11)
	v_mfma_f32_16x16x32_bf16 v[36:39], v[126:129], v[102:105], v[36:39]
	s_waitcnt lgkmcnt(10)
	v_mfma_f32_16x16x32_bf16 v[32:35], v[130:133], v[102:105], v[32:35]
	v_mfma_f32_16x16x32_bf16 v[28:31], v[94:97], v[106:109], v[28:31]
	v_mfma_f32_16x16x32_bf16 v[24:27], v[98:101], v[106:109], v[24:27]
	v_mfma_f32_16x16x32_bf16 v[20:23], v[110:113], v[106:109], v[20:23]
	v_mfma_f32_16x16x32_bf16 v[12:15], v[114:117], v[106:109], v[12:15]
	v_mfma_f32_16x16x32_bf16 v[8:11], v[118:121], v[106:109], v[8:11]
	v_mfma_f32_16x16x32_bf16 v[4:7], v[122:125], v[106:109], v[4:7]
	v_mfma_f32_16x16x32_bf16 v[0:3], v[126:129], v[106:109], v[0:3]
	v_mfma_f32_16x16x32_bf16 v[16:19], v[130:133], v[106:109], v[16:19]
	s_waitcnt lgkmcnt(8)
	v_mfma_f32_16x16x32_bf16 v[60:63], v[166:169], v[174:177], v[60:63]
	s_waitcnt lgkmcnt(7)
	v_mfma_f32_16x16x32_bf16 v[56:59], v[170:173], v[174:177], v[56:59]
	s_waitcnt lgkmcnt(5)
	v_mfma_f32_16x16x32_bf16 v[52:55], v[182:185], v[174:177], v[52:55]
	s_waitcnt lgkmcnt(4)
	v_mfma_f32_16x16x32_bf16 v[48:51], v[186:189], v[174:177], v[48:51]
	s_waitcnt lgkmcnt(3)
	v_mfma_f32_16x16x32_bf16 v[44:47], v[190:193], v[174:177], v[44:47]
	s_waitcnt lgkmcnt(2)
	v_mfma_f32_16x16x32_bf16 v[40:43], v[194:197], v[174:177], v[40:43]
	s_waitcnt lgkmcnt(1)
	v_mfma_f32_16x16x32_bf16 v[36:39], v[198:201], v[174:177], v[36:39]
	s_waitcnt lgkmcnt(0)
	v_mfma_f32_16x16x32_bf16 v[32:35], v[202:205], v[174:177], v[32:35]
	v_mfma_f32_16x16x32_bf16 v[28:31], v[166:169], v[178:181], v[28:31]
	v_mfma_f32_16x16x32_bf16 v[24:27], v[170:173], v[178:181], v[24:27]
	v_mfma_f32_16x16x32_bf16 v[20:23], v[182:185], v[178:181], v[20:23]
	v_mfma_f32_16x16x32_bf16 v[12:15], v[186:189], v[178:181], v[12:15]
	v_mfma_f32_16x16x32_bf16 v[8:11], v[190:193], v[178:181], v[8:11]
	v_mfma_f32_16x16x32_bf16 v[4:7], v[194:197], v[178:181], v[4:7]
	v_mfma_f32_16x16x32_bf16 v[0:3], v[198:201], v[178:181], v[0:3]
	v_mfma_f32_16x16x32_bf16 v[16:19], v[202:205], v[178:181], v[16:19]
	s_cbranch_scc0 .LBB0_1759
	v_add_u32_e32 v138, s35, v80
	v_add_u32_e32 v126, v138, v81
	s_waitcnt vmcnt(0)
	s_barrier
	ds_read_b128 v[74:77], v126 offset:16384
	v_add3_u32 v102, s35, v81, v82
	ds_read_b128 v[94:97], v102
	ds_read_b128 v[98:101], v126 offset:18432
	ds_read_b128 v[102:105], v102 offset:2048
	ds_read_b128 v[106:109], v126 offset:20480
	ds_read_b128 v[110:113], v126 offset:22528
	ds_read_b128 v[114:117], v126 offset:24576
	ds_read_b128 v[118:121], v126 offset:26624
	v_add3_u32 v134, s35, v83, v82
	v_add_u32_e32 v142, v138, v83
	ds_read_b128 v[122:125], v126 offset:28672
	ds_read_b128 v[126:129], v126 offset:30720
	ds_read_b128 v[130:133], v134
	ds_read_b128 v[134:137], v134 offset:2048
	ds_read_b128 v[138:141], v142 offset:16384
	ds_read_b128 v[146:149], v142 offset:18432
	s_waitcnt lgkmcnt(11)
	v_mfma_f32_16x16x32_bf16 v[56:59], v[98:101], v[94:97], v[56:59]
	s_lshl_b32 s33, s33, 7
	s_lshl_b32 s26, s31, 7
	s_ashr_i32 s27, s26, 31
	v_mfma_f32_16x16x32_bf16 v[60:63], v[74:77], v[94:97], v[60:63]
	s_lshl_b64 s[26:27], s[26:27], 1
	s_add_i32 s30, s30, s28
	s_cmpk_gt_i32 s30, 0xfff
	s_waitcnt lgkmcnt(0)
	v_mfma_f32_16x16x32_bf16 v[56:59], v[146:149], v[130:133], v[56:59]
	v_mfma_f32_16x16x32_bf16 v[48:51], v[110:113], v[94:97], v[48:51]
	v_mfma_f32_16x16x32_bf16 v[52:55], v[106:109], v[94:97], v[52:55]
	s_nop 5
	v_max_f32_e32 v56, v56, v56
	v_max_f32_e32 v57, v57, v57
	v_max_f32_e32 v56, 0, v56
	v_mfma_f32_16x16x32_bf16 v[44:47], v[114:117], v[94:97], v[44:47]
	v_max_f32_e32 v57, 0, v57
	v_max_f32_e32 v59, v59, v59
	v_max_f32_e32 v59, 0, v59
	v_mfma_f32_16x16x32_bf16 v[40:43], v[118:121], v[94:97], v[40:43]
	v_mfma_f32_16x16x32_bf16 v[36:39], v[122:125], v[94:97], v[36:39]
	v_mfma_f32_16x16x32_bf16 v[32:35], v[126:129], v[94:97], v[32:35]
	ds_read_b128 v[94:97], v142 offset:20480
	ds_read_b128 v[150:153], v142 offset:22528
	ds_read_b128 v[154:157], v142 offset:24576
	ds_read_b128 v[158:161], v142 offset:26624
	v_mfma_f32_16x16x32_bf16 v[60:63], v[138:141], v[130:133], v[60:63]
	s_waitcnt lgkmcnt(2)
	v_mfma_f32_16x16x32_bf16 v[48:51], v[150:153], v[130:133], v[48:51]
	v_mfma_f32_16x16x32_bf16 v[20:23], v[106:109], v[102:105], v[20:23]
	v_mul_f32_e64 v106, v56, v56
	v_mul_f32_e64 v107, v57, v57
	v_max_f32_e32 v57, v58, v58
	s_nop 1
	v_max_f32_e32 v60, v60, v60
	v_mfma_f32_16x16x32_bf16 v[24:27], v[98:101], v[102:105], v[24:27]
	v_add_u32_e32 v100, s33, v79
	v_mov_b64_e32 v[98:99], s[0:1]
	v_max_f32_e32 v61, v61, v61
	v_max_f32_e32 v56, v62, v62
	v_max_f32_e32 v58, 0, v57
	v_max_f32_e32 v57, v63, v63
	v_mad_i64_i32 v[100:101], s[34:35], v100, s29, v[98:99]
	v_max_f32_e32 v60, 0, v60
	v_max_f32_e32 v61, 0, v61
	v_max_f32_e32 v56, 0, v56
	v_max_f32_e32 v57, 0, v57
	v_mfma_f32_16x16x32_bf16 v[52:55], v[94:97], v[130:133], v[52:55]
	v_lshl_add_u64 v[100:101], v[100:101], 0, s[26:27]
	v_pk_mul_f32 v[60:61], v[60:61], v[60:61]
	v_pk_mul_f32 v[62:63], v[56:57], v[56:57]
	v_mfma_f32_16x16x32_bf16 v[28:31], v[74:77], v[102:105], v[28:31]
	v_max_f32_e32 v48, v48, v48
	v_max_f32_e32 v49, v49, v49
	ds_read_b128 v[74:77], v142 offset:28672
	ds_read_b128 v[162:165], v142 offset:30720
	v_mfma_f32_16x16x32_bf16 v[12:15], v[110:113], v[102:105], v[12:15]
	v_lshl_add_u64 v[100:101], v[100:101], 0, v[64:65]
	v_cvt_pk_bf16_f32 v56, v60, v61
	v_cvt_pk_bf16_f32 v57, v62, v63
	v_mfma_f32_16x16x32_bf16 v[8:11], v[114:117], v[102:105], v[8:11]
	v_max_f32_e32 v48, 0, v48
	v_max_f32_e32 v49, 0, v49
	v_max_f32_e32 v52, v52, v52
	v_mfma_f32_16x16x32_bf16 v[4:7], v[118:121], v[102:105], v[4:7]
	v_max_f32_e32 v53, v53, v53
	v_max_f32_e32 v51, v51, v51
	v_max_f32_e32 v52, 0, v52
	v_mfma_f32_16x16x32_bf16 v[0:3], v[122:125], v[102:105], v[0:3]
	v_max_f32_e32 v53, 0, v53
	v_max_f32_e32 v51, 0, v51
	v_pk_mul_f32 v[52:53], v[52:53], v[52:53]
	v_mfma_f32_16x16x32_bf16 v[16:19], v[126:129], v[102:105], v[16:19]
	v_mul_f32_e64 v102, v58, v58
	v_mul_f32_e64 v103, v59, v59
	v_cvt_pk_bf16_f32 v58, v106, v107
	v_cvt_pk_bf16_f32 v59, v102, v103
	s_waitcnt lgkmcnt(2)
	v_mfma_f32_16x16x32_bf16 v[40:43], v[158:161], v[130:133], v[40:43]
	global_store_dwordx4 v[100:101], v[56:59], off
	s_nop 1
	v_pk_mul_f32 v[56:57], v[48:49], v[48:49]
	v_max_f32_e32 v49, v50, v50
	v_max_f32_e32 v48, v54, v54
	v_max_f32_e32 v50, 0, v49
	v_max_f32_e32 v49, v55, v55
	v_mfma_f32_16x16x32_bf16 v[44:47], v[154:157], v[130:133], v[44:47]
	v_max_f32_e32 v48, 0, v48
	v_max_f32_e32 v49, 0, v49
	v_pk_mul_f32 v[54:55], v[48:49], v[48:49]
	v_pk_mul_f32 v[58:59], v[50:51], v[50:51]
	v_max_f32_e32 v40, v40, v40
	v_max_f32_e32 v41, v41, v41
	s_waitcnt lgkmcnt(0)
	v_mfma_f32_16x16x32_bf16 v[32:35], v[162:165], v[130:133], v[32:35]
	v_cvt_pk_bf16_f32 v48, v52, v53
	v_cvt_pk_bf16_f32 v49, v54, v55
	v_cvt_pk_bf16_f32 v50, v56, v57
	v_cvt_pk_bf16_f32 v51, v58, v59
	v_max_f32_e32 v40, 0, v40
	v_max_f32_e32 v41, 0, v41
	global_store_dwordx4 v[100:101], v[48:51], off offset:64
	v_max_f32_e32 v44, v44, v44
	v_max_f32_e32 v45, v45, v45
	v_pk_mul_f32 v[48:49], v[40:41], v[40:41]
	v_max_f32_e32 v41, v42, v42
	v_max_f32_e32 v40, v46, v46
	v_max_f32_e32 v42, 0, v41
	v_max_f32_e32 v41, v47, v47
	v_max_f32_e32 v43, v43, v43
	v_mfma_f32_16x16x32_bf16 v[36:39], v[74:77], v[130:133], v[36:39]
	v_max_f32_e32 v44, 0, v44
	v_max_f32_e32 v45, 0, v45
	v_max_f32_e32 v40, 0, v40
	v_max_f32_e32 v41, 0, v41
	v_max_f32_e32 v43, 0, v43
	v_pk_mul_f32 v[44:45], v[44:45], v[44:45]
	v_pk_mul_f32 v[46:47], v[40:41], v[40:41]
	v_pk_mul_f32 v[50:51], v[42:43], v[42:43]
	v_max_f32_e32 v32, v32, v32
	v_max_f32_e32 v33, v33, v33
	v_mfma_f32_16x16x32_bf16 v[24:27], v[146:149], v[134:137], v[24:27]
	v_cvt_pk_bf16_f32 v40, v44, v45
	v_cvt_pk_bf16_f32 v41, v46, v47
	v_cvt_pk_bf16_f32 v42, v48, v49
	v_cvt_pk_bf16_f32 v43, v50, v51
	v_max_f32_e32 v32, 0, v32
	v_max_f32_e32 v33, 0, v33
	global_store_dwordx4 v[100:101], v[40:43], off offset:128
	v_max_f32_e32 v36, v36, v36
	v_max_f32_e32 v37, v37, v37
	v_pk_mul_f32 v[40:41], v[32:33], v[32:33]
	v_max_f32_e32 v33, v34, v34
	v_max_f32_e32 v32, v38, v38
	v_max_f32_e32 v34, 0, v33
	v_max_f32_e32 v33, v39, v39
	v_max_f32_e32 v35, v35, v35
	v_mfma_f32_16x16x32_bf16 v[28:31], v[138:141], v[134:137], v[28:31]
	v_max_f32_e32 v36, 0, v36
	v_max_f32_e32 v37, 0, v37
	v_max_f32_e32 v32, 0, v32
	v_max_f32_e32 v33, 0, v33
	v_max_f32_e32 v35, 0, v35
	v_pk_mul_f32 v[36:37], v[36:37], v[36:37]
	v_pk_mul_f32 v[38:39], v[32:33], v[32:33]
	v_pk_mul_f32 v[42:43], v[34:35], v[34:35]
	v_max_f32_e32 v24, v24, v24
	v_max_f32_e32 v25, v25, v25
	v_mfma_f32_16x16x32_bf16 v[12:15], v[150:153], v[134:137], v[12:15]
	v_cvt_pk_bf16_f32 v32, v36, v37
	v_cvt_pk_bf16_f32 v33, v38, v39
	v_cvt_pk_bf16_f32 v34, v40, v41
	v_cvt_pk_bf16_f32 v35, v42, v43
	v_max_f32_e32 v24, 0, v24
	v_max_f32_e32 v25, 0, v25
	global_store_dwordx4 v[100:101], v[32:35], off offset:192
	v_max_f32_e32 v28, v28, v28
	v_max_f32_e32 v29, v29, v29
	v_pk_mul_f32 v[34:35], v[24:25], v[24:25]
	v_max_f32_e32 v25, v26, v26
	v_add_u32_e32 v32, s33, v84
	v_max_f32_e32 v24, v30, v30
	v_max_f32_e32 v26, 0, v25
	v_max_f32_e32 v25, v31, v31
	v_max_f32_e32 v27, v27, v27
	v_mfma_f32_16x16x32_bf16 v[20:23], v[94:97], v[134:137], v[20:23]
	v_mad_i64_i32 v[32:33], s[34:35], v32, s29, v[98:99]
	v_max_f32_e32 v28, 0, v28
	v_max_f32_e32 v29, 0, v29
	v_max_f32_e32 v24, 0, v24
	v_max_f32_e32 v25, 0, v25
	v_max_f32_e32 v27, 0, v27
	v_lshl_add_u64 v[32:33], v[32:33], 0, s[26:27]
	v_pk_mul_f32 v[28:29], v[28:29], v[28:29]
	v_pk_mul_f32 v[30:31], v[24:25], v[24:25]
	v_pk_mul_f32 v[36:37], v[26:27], v[26:27]
	v_max_f32_e32 v12, v12, v12
	v_max_f32_e32 v13, v13, v13
	v_mfma_f32_16x16x32_bf16 v[4:7], v[158:161], v[134:137], v[4:7]
	v_lshl_add_u64 v[32:33], v[32:33], 0, v[64:65]
	v_cvt_pk_bf16_f32 v24, v28, v29
	v_cvt_pk_bf16_f32 v25, v30, v31
	v_cvt_pk_bf16_f32 v26, v34, v35
	v_cvt_pk_bf16_f32 v27, v36, v37
	v_max_f32_e32 v12, 0, v12
	v_max_f32_e32 v13, 0, v13
	global_store_dwordx4 v[32:33], v[24:27], off
	v_max_f32_e32 v20, v20, v20
	v_max_f32_e32 v21, v21, v21
	v_pk_mul_f32 v[24:25], v[12:13], v[12:13]
	v_max_f32_e32 v13, v14, v14
	v_max_f32_e32 v12, v22, v22
	v_max_f32_e32 v14, 0, v13
	v_max_f32_e32 v13, v23, v23
	v_max_f32_e32 v15, v15, v15
	v_mfma_f32_16x16x32_bf16 v[8:11], v[154:157], v[134:137], v[8:11]
	v_max_f32_e32 v20, 0, v20
	v_max_f32_e32 v21, 0, v21
	v_max_f32_e32 v12, 0, v12
	v_max_f32_e32 v13, 0, v13
	v_max_f32_e32 v15, 0, v15
	v_pk_mul_f32 v[20:21], v[20:21], v[20:21]
	v_pk_mul_f32 v[22:23], v[12:13], v[12:13]
	v_pk_mul_f32 v[26:27], v[14:15], v[14:15]
	v_max_f32_e32 v4, v4, v4
	v_max_f32_e32 v5, v5, v5
	v_cvt_pk_bf16_f32 v12, v20, v21
	v_cvt_pk_bf16_f32 v13, v22, v23
	v_cvt_pk_bf16_f32 v14, v24, v25
	v_cvt_pk_bf16_f32 v15, v26, v27
	v_max_f32_e32 v4, 0, v4
	v_max_f32_e32 v5, 0, v5
	global_store_dwordx4 v[32:33], v[12:15], off offset:64
	v_mfma_f32_16x16x32_bf16 v[0:3], v[74:77], v[134:137], v[0:3]
	v_max_f32_e32 v8, v8, v8
	v_pk_mul_f32 v[12:13], v[4:5], v[4:5]
	v_max_f32_e32 v5, v6, v6
	v_mfma_f32_16x16x32_bf16 v[16:19], v[162:165], v[134:137], v[16:19]
	v_max_f32_e32 v9, v9, v9
	v_max_f32_e32 v4, v10, v10
	v_max_f32_e32 v6, 0, v5
	v_max_f32_e32 v5, v11, v11
	v_max_f32_e32 v7, v7, v7
	v_max_f32_e32 v8, 0, v8
	v_max_f32_e32 v9, 0, v9
	v_max_f32_e32 v4, 0, v4
	v_max_f32_e32 v5, 0, v5
	v_max_f32_e32 v7, 0, v7
	v_pk_mul_f32 v[8:9], v[8:9], v[8:9]
	v_pk_mul_f32 v[10:11], v[4:5], v[4:5]
	v_pk_mul_f32 v[14:15], v[6:7], v[6:7]
	v_cvt_pk_bf16_f32 v4, v8, v9
	v_cvt_pk_bf16_f32 v5, v10, v11
	v_cvt_pk_bf16_f32 v6, v12, v13
	v_cvt_pk_bf16_f32 v7, v14, v15
	global_store_dwordx4 v[32:33], v[4:7], off offset:128
	v_max_f32_e32 v0, v0, v0
	v_max_f32_e32 v1, v1, v1
	v_max_f32_e32 v4, v16, v16
	v_max_f32_e32 v5, v17, v17
	v_max_f32_e32 v2, v2, v2
	v_max_f32_e32 v6, v18, v18
	v_max_f32_e32 v3, v3, v3
	v_max_f32_e32 v7, v19, v19
	v_max_f32_e32 v0, 0, v0
	v_max_f32_e32 v4, 0, v4
	v_max_f32_e32 v1, 0, v1
	v_max_f32_e32 v5, 0, v5
	v_max_f32_e32 v2, 0, v2
	v_max_f32_e32 v6, 0, v6
	v_max_f32_e32 v3, 0, v3
	v_max_f32_e32 v7, 0, v7
	v_pk_mul_f32 v[0:1], v[0:1], v[0:1]
	v_pk_mul_f32 v[4:5], v[4:5], v[4:5]
	v_pk_mul_f32 v[2:3], v[2:3], v[2:3]
	v_pk_mul_f32 v[6:7], v[6:7], v[6:7]
	v_cvt_pk_bf16_f32 v0, v0, v1
	v_cvt_pk_bf16_f32 v1, v2, v3
	v_cvt_pk_bf16_f32 v2, v4, v5
	v_cvt_pk_bf16_f32 v3, v6, v7
	global_store_dwordx4 v[32:33], v[0:3], off offset:192
	s_cbranch_scc0 .LBB0_1754

.LBB0_1824:
	s_add_i32 s41, s39, 0x8000
	s_and_b32 s40, s41, 0x8000
	s_add_i32 s40, s40, 0
	s_add_u32 s86, s40, s87
	s_mov_b32 m0, s86
	s_waitcnt vmcnt(0) lgkmcnt(0)
	s_barrier
	global_load_lds_dwordx4 v244, s[96:97]
	s_add_u32 m0, s86, 0x4000
	s_nop 0
	global_load_lds_dwordx4 v245, s[88:89]
	s_add_u32 m0, s86, 0x1000
	s_nop 0
	global_load_lds_dwordx4 v246, s[96:97]
	s_add_u32 m0, s86, 0x5000
	s_nop 0
	global_load_lds_dwordx4 v247, s[88:89]
	s_add_u32 m0, s86, 0x2000
	s_nop 0
	global_load_lds_dwordx4 v248, s[96:97]
	s_add_u32 m0, s86, 0x6000
	s_nop 0
	global_load_lds_dwordx4 v249, s[88:89]
	s_add_u32 m0, s86, 0x3000
	s_nop 0
	global_load_lds_dwordx4 v250, s[96:97]
	s_add_u32 m0, s86, 0x7000
	s_nop 0
	global_load_lds_dwordx4 v251, s[88:89]
	s_add_u32 s96, s96, 0x80
	s_addc_u32 s97, s97, 0
	s_add_u32 s88, s88, 0x80
	s_addc_u32 s89, s89, 0
	s_and_b32 s39, s39, 0x8000
	s_add_i32 s39, s39, 0
	v_add3_u32 v145, s39, v84, v85
	v_add3_u32 v178, s39, v85, v86
	v_add3_u32 v179, s39, v84, v87
	v_add3_u32 v180, s39, v86, v87
	ds_read_b128 v[104:107], v178
	ds_read_b128 v[76:79], v145 offset:16384
	ds_read_b128 v[100:103], v145 offset:18432
	ds_read_b128 v[108:111], v178 offset:2048
	ds_read_b128 v[112:115], v145 offset:20480
	ds_read_b128 v[116:119], v145 offset:22528
	ds_read_b128 v[120:123], v145 offset:24576
	ds_read_b128 v[124:127], v145 offset:26624
	ds_read_b128 v[128:131], v145 offset:28672
	ds_read_b128 v[132:135], v145 offset:30720
	ds_read_b128 v[146:149], v180
	ds_read_b128 v[136:139], v179 offset:16384
	ds_read_b128 v[140:143], v179 offset:18432
	ds_read_b128 v[150:153], v180 offset:2048
	ds_read_b128 v[154:157], v179 offset:20480
	ds_read_b128 v[158:161], v179 offset:22528
	ds_read_b128 v[162:165], v179 offset:24576
	ds_read_b128 v[166:169], v179 offset:26624
	ds_read_b128 v[170:173], v179 offset:28672
	ds_read_b128 v[174:177], v179 offset:30720
	s_add_u32 s28, s28, 0x80
	s_addc_u32 s29, s29, 0
	s_cmpk_eq_i32 s28, 0x1f80
	s_mov_b32 s39, s41
	s_waitcnt lgkmcnt(15)
	v_mfma_f32_16x16x32_bf16 v[60:63], v[76:79], v[104:107], v[60:63]
	v_mfma_f32_16x16x32_bf16 v[56:59], v[100:103], v[104:107], v[56:59]
	v_mfma_f32_16x16x32_bf16 v[52:55], v[112:115], v[104:107], v[52:55]
	s_waitcnt lgkmcnt(14)
	v_mfma_f32_16x16x32_bf16 v[48:51], v[116:119], v[104:107], v[48:51]
	s_waitcnt lgkmcnt(13)
	v_mfma_f32_16x16x32_bf16 v[44:47], v[120:123], v[104:107], v[44:47]
	s_waitcnt lgkmcnt(12)
	v_mfma_f32_16x16x32_bf16 v[40:43], v[124:127], v[104:107], v[40:43]
	s_waitcnt lgkmcnt(11)
	v_mfma_f32_16x16x32_bf16 v[32:35], v[128:131], v[104:107], v[32:35]
	s_waitcnt lgkmcnt(10)
	v_mfma_f32_16x16x32_bf16 v[28:31], v[132:135], v[104:107], v[28:31]
	v_mfma_f32_16x16x32_bf16 v[24:27], v[76:79], v[108:111], v[24:27]
	v_mfma_f32_16x16x32_bf16 v[20:23], v[100:103], v[108:111], v[20:23]
	v_mfma_f32_16x16x32_bf16 v[16:19], v[112:115], v[108:111], v[16:19]
	v_mfma_f32_16x16x32_bf16 v[12:15], v[116:119], v[108:111], v[12:15]
	v_mfma_f32_16x16x32_bf16 v[8:11], v[120:123], v[108:111], v[8:11]
	v_mfma_f32_16x16x32_bf16 v[4:7], v[124:127], v[108:111], v[4:7]
	v_mfma_f32_16x16x32_bf16 v[0:3], v[128:131], v[108:111], v[0:3]
	v_mfma_f32_16x16x32_bf16 v[36:39], v[132:135], v[108:111], v[36:39]
	s_waitcnt lgkmcnt(8)
	v_mfma_f32_16x16x32_bf16 v[60:63], v[136:139], v[146:149], v[60:63]
	s_waitcnt lgkmcnt(7)
	v_mfma_f32_16x16x32_bf16 v[56:59], v[140:143], v[146:149], v[56:59]
	s_waitcnt lgkmcnt(5)
	v_mfma_f32_16x16x32_bf16 v[52:55], v[154:157], v[146:149], v[52:55]
	s_waitcnt lgkmcnt(4)
	v_mfma_f32_16x16x32_bf16 v[48:51], v[158:161], v[146:149], v[48:51]
	s_waitcnt lgkmcnt(3)
	v_mfma_f32_16x16x32_bf16 v[44:47], v[162:165], v[146:149], v[44:47]
	s_waitcnt lgkmcnt(2)
	v_mfma_f32_16x16x32_bf16 v[40:43], v[166:169], v[146:149], v[40:43]
	s_waitcnt lgkmcnt(1)
	v_mfma_f32_16x16x32_bf16 v[32:35], v[170:173], v[146:149], v[32:35]
	s_waitcnt lgkmcnt(0)
	v_mfma_f32_16x16x32_bf16 v[28:31], v[174:177], v[146:149], v[28:31]
	v_mfma_f32_16x16x32_bf16 v[24:27], v[136:139], v[150:153], v[24:27]
	v_mfma_f32_16x16x32_bf16 v[20:23], v[140:143], v[150:153], v[20:23]
	v_mfma_f32_16x16x32_bf16 v[16:19], v[154:157], v[150:153], v[16:19]
	v_mfma_f32_16x16x32_bf16 v[12:15], v[158:161], v[150:153], v[12:15]
	v_mfma_f32_16x16x32_bf16 v[8:11], v[162:165], v[150:153], v[8:11]
	v_mfma_f32_16x16x32_bf16 v[4:7], v[166:169], v[150:153], v[4:7]
	v_mfma_f32_16x16x32_bf16 v[0:3], v[170:173], v[150:153], v[0:3]
	v_mfma_f32_16x16x32_bf16 v[36:39], v[174:177], v[150:153], v[36:39]
	s_cbranch_scc0 .LBB0_1824
	v_add_u32_e32 v80, s40, v84
	v_add_u32_e32 v81, v80, v85
	s_waitcnt vmcnt(0)
	s_barrier
	ds_read_b128 v[72:75], v81 offset:16384
	v_add3_u32 v99, s40, v85, v86
	ds_read_b128 v[76:79], v81 offset:18432
	ds_read_b128 v[100:103], v99
	ds_read_b128 v[104:107], v99 offset:2048
	ds_read_b128 v[108:111], v81 offset:20480
	ds_read_b128 v[112:115], v81 offset:22528
	ds_read_b128 v[116:119], v81 offset:24576
	ds_read_b128 v[120:123], v81 offset:26624
	ds_read_b128 v[124:127], v81 offset:28672
	ds_read_b128 v[128:131], v81 offset:30720
	v_add_u32_e32 v80, v80, v87
	s_waitcnt lgkmcnt(7)
	v_mfma_f32_16x16x32_bf16 v[60:63], v[72:75], v[100:103], v[60:63]
	s_lshl_b32 s38, s38, 7
	v_mfma_f32_16x16x32_bf16 v[56:59], v[76:79], v[100:103], v[56:59]
	s_waitcnt lgkmcnt(4)
	v_mfma_f32_16x16x32_bf16 v[48:51], v[112:115], v[100:103], v[48:51]
	s_waitcnt lgkmcnt(3)
	v_mfma_f32_16x16x32_bf16 v[44:47], v[116:119], v[100:103], v[44:47]
	s_waitcnt lgkmcnt(2)
	v_mfma_f32_16x16x32_bf16 v[40:43], v[120:123], v[100:103], v[40:43]
	s_waitcnt lgkmcnt(1)
	v_mfma_f32_16x16x32_bf16 v[32:35], v[124:127], v[100:103], v[32:35]
	s_waitcnt lgkmcnt(0)
	v_mfma_f32_16x16x32_bf16 v[28:31], v[128:131], v[100:103], v[28:31]
	v_mfma_f32_16x16x32_bf16 v[24:27], v[72:75], v[104:107], v[24:27]
	ds_read_b128 v[72:75], v80 offset:16384
	v_mfma_f32_16x16x32_bf16 v[52:55], v[108:111], v[100:103], v[52:55]
	v_mfma_f32_16x16x32_bf16 v[20:23], v[76:79], v[104:107], v[20:23]
	v_mfma_f32_16x16x32_bf16 v[16:19], v[108:111], v[104:107], v[16:19]
	v_mfma_f32_16x16x32_bf16 v[12:15], v[112:115], v[104:107], v[12:15]
	v_mfma_f32_16x16x32_bf16 v[8:11], v[116:119], v[104:107], v[8:11]
	v_mfma_f32_16x16x32_bf16 v[4:7], v[120:123], v[104:107], v[4:7]
	v_mfma_f32_16x16x32_bf16 v[0:3], v[124:127], v[104:107], v[0:3]
	v_mfma_f32_16x16x32_bf16 v[100:103], v[128:131], v[104:107], v[36:39]
	s_nop 2
	v_add3_u32 v36, s40, v87, v86
	ds_read_b128 v[76:79], v80 offset:18432
	ds_read_b128 v[104:107], v36
	ds_read_b128 v[108:111], v36 offset:2048
	ds_read_b128 v[128:131], v80 offset:28672
	ds_read_b128 v[132:135], v80 offset:30720
	ds_read_b128 v[112:115], v80 offset:20480
	ds_read_b128 v[116:119], v80 offset:22528
	ds_read_b128 v[120:123], v80 offset:24576
	ds_read_b128 v[124:127], v80 offset:26624
	s_waitcnt lgkmcnt(7)
	v_mfma_f32_16x16x32_bf16 v[60:63], v[72:75], v[104:107], v[60:63]
	s_waitcnt lgkmcnt(5)
	v_mfma_f32_16x16x32_bf16 v[36:39], v[128:131], v[104:107], v[32:35]
	s_waitcnt lgkmcnt(4)
	v_mfma_f32_16x16x32_bf16 v[32:35], v[132:135], v[104:107], v[28:31]
	v_mfma_f32_16x16x32_bf16 v[28:31], v[72:75], v[108:111], v[24:27]
	v_add_u32_e32 v72, s38, v83
	v_mul_hi_i32 v73, v72, s31
	v_mfma_f32_16x16x32_bf16 v[24:27], v[76:79], v[108:111], v[20:23]
	s_waitcnt lgkmcnt(3)
	v_mfma_f32_16x16x32_bf16 v[20:23], v[112:115], v[108:111], v[16:19]
	s_waitcnt lgkmcnt(2)
	v_mfma_f32_16x16x32_bf16 v[16:19], v[116:119], v[108:111], v[12:15]
	s_waitcnt lgkmcnt(1)
	v_mfma_f32_16x16x32_bf16 v[12:15], v[120:123], v[108:111], v[8:11]
	s_waitcnt lgkmcnt(0)
	v_mfma_f32_16x16x32_bf16 v[8:11], v[124:127], v[108:111], v[4:7]
	s_nop 2
	v_lshrrev_b32_e32 v4, 31, v73
	v_ashrrev_i32_e32 v5, 11, v73
	v_mfma_f32_16x16x32_bf16 v[56:59], v[76:79], v[104:107], v[56:59]
	v_add_u32_e32 v73, v5, v4
	v_mad_i32_i24 v78, v73, s33, v72
	v_lshlrev_b32_e32 v75, 13, v73
	v_mfma_f32_16x16x32_bf16 v[52:55], v[112:115], v[104:107], v[52:55]
	v_cmp_lt_i32_e32 vcc, s34, v78
	v_add3_u32 v74, v75, v78, s35
	v_mfma_f32_16x16x32_bf16 v[48:51], v[116:119], v[104:107], v[48:51]
	v_mfma_f32_16x16x32_bf16 v[44:47], v[120:123], v[104:107], v[44:47]
	v_mfma_f32_16x16x32_bf16 v[40:43], v[124:127], v[104:107], v[40:43]
	v_mfma_f32_16x16x32_bf16 v[4:7], v[128:131], v[108:111], v[0:3]
	v_mfma_f32_16x16x32_bf16 v[0:3], v[132:135], v[108:111], v[100:103]
	s_and_saveexec_b64 s[28:29], vcc
	s_xor_b64 s[28:29], exec, s[28:29]
	v_add3_u32 v72, v75, v78, s35
	s_or_saveexec_b64 s[28:29], s[28:29]
	v_mov_b64_e32 v[76:77], s[92:93]
	v_lshl_add_u32 v75, v73, 8, v78
	s_xor_b64 exec, exec, s[28:29]
	v_lshl_add_u32 v72, v73, 8, v78
	v_mov_b64_e32 v[76:77], s[2:3]
	s_or_b64 exec, exec, s[28:29]
	s_and_saveexec_b64 s[28:29], vcc
	s_xor_b64 s[28:29], exec, s[28:29]
	s_cbranch_execz .LBB0_1831
	v_add_u32_e32 v73, 3, v73
	v_mul_hi_i32_i24_e32 v79, 0x6000, v73
	v_mul_i32_i24_e32 v78, 0x6000, v73
	s_or_saveexec_b64 s[28:29], s[28:29]
	v_mov_b64_e32 v[80:81], s[92:93]
	s_xor_b64 exec, exec, s[28:29]
	s_cbranch_execnz .LBB0_1832
	s_branch .LBB0_1833
